# rwprep stage3: row loads prefetched two tokens ahead with two alternating VGPR buffers (counted vmcnt 16)
# speedup vs baseline: 1.0108x; 1.0108x over previous
.LBB0_195:
	s_or_b64 exec, exec, s[16:17]
	v_add_u32_e32 v102, s20, v133
	v_mad_i64_i32 v[52:53], s[10:11], v102, s22, v[60:61]
	global_load_dwordx2 v[104:105], v[52:53], off
	global_load_dwordx2 v[120:121], v[52:53], off offset:2048
	v_add_co_u32_e32 v52, vcc, s2, v52
	s_waitcnt vmcnt(1)
	v_lshlrev_b32_e32 v118, 16, v104
	v_addc_co_u32_e32 v53, vcc, 0, v53, vcc
	global_load_dwordx2 v[108:109], v[52:53], off
	global_load_dwordx2 v[116:117], v[52:53], off offset:2048
	v_add_u32_e32 v242, 1, v102
	v_mad_i64_i32 v[242:243], s[26:27], v242, s22, v[60:61]
	global_load_dwordx2 v[246:247], v[242:243], off
	global_load_dwordx2 v[248:249], v[242:243], off offset:2048
	v_add_co_u32_e32 v244, vcc, s2, v242
	s_nop 1
	v_addc_co_u32_e32 v245, vcc, 0, v243, vcc
	global_load_dwordx2 v[250:251], v[244:245], off
	global_load_dwordx2 v[254:255], v[244:245], off offset:2048
	v_add_u32_e32 v242, 2, v102
	v_mad_i64_i32 v[242:243], s[26:27], v242, s22, v[60:61]
	global_load_dwordx2 v[234:235], v[242:243], off
	global_load_dwordx2 v[236:237], v[242:243], off offset:2048
	v_add_co_u32_e32 v244, vcc, s2, v242
	s_nop 1
	v_addc_co_u32_e32 v245, vcc, 0, v243, vcc
	global_load_dwordx2 v[238:239], v[244:245], off
	global_load_dwordx2 v[240:241], v[244:245], off offset:2048
	ds_read2st64_b64 v[52:55], v166 offset0:16 offset1:80
	v_and_b32_e32 v119, 0xffff0000, v104
	s_waitcnt vmcnt(10)
	v_lshlrev_b32_e32 v114, 16, v120
	v_and_b32_e32 v115, 0xffff0000, v120
	v_pk_add_f32 v[44:45], v[44:45], v[118:119] neg_lo:[0,1] neg_hi:[0,1]
	s_waitcnt lgkmcnt(0)
	v_lshlrev_b32_e32 v58, 16, v54
	v_and_b32_e32 v54, 0xffff0000, v54
	v_lshlrev_b32_e32 v103, 16, v55
	v_and_b32_e32 v55, 0xffff0000, v55
	v_add_f32_e32 v58, v12, v58
	v_add_f32_e32 v54, v13, v54
	v_add_f32_e32 v103, v14, v103
	v_add_f32_e32 v55, v15, v55
	v_mul_f32_e32 v58, 0xbfb8aa3b, v58
	v_mul_f32_e32 v54, 0xbfb8aa3b, v54
	v_mul_f32_e32 v103, 0xbfb8aa3b, v103
	v_mul_f32_e32 v55, 0xbfb8aa3b, v55
	v_exp_f32_e32 v58, v58
	v_exp_f32_e32 v54, v54
	v_exp_f32_e32 v103, v103
	v_exp_f32_e32 v55, v55
	v_add_f32_e32 v58, 1.0, v58
	v_add_f32_e32 v54, 1.0, v54
	v_add_f32_e32 v103, 1.0, v103
	v_add_f32_e32 v55, 1.0, v55
	v_rcp_f32_e32 v112, v58
	v_rcp_f32_e32 v113, v54
	v_rcp_f32_e32 v110, v103
	v_rcp_f32_e32 v111, v55
	v_pk_add_f32 v[48:49], v[48:49], v[114:115] neg_lo:[0,1] neg_hi:[0,1]
	v_pk_add_f32 v[54:55], v[112:113], -1.0 op_sel_hi:[1,0]
	v_pk_fma_f32 v[122:123], v[16:17], v[44:45], v[118:119]
	v_pk_add_f32 v[106:107], v[110:111], -1.0 op_sel_hi:[1,0]
	v_pk_fma_f32 v[124:125], v[28:29], v[54:55], 1.0 op_sel_hi:[1,1,0]
	v_lshlrev_b32_e32 v54, 16, v121
	v_and_b32_e32 v55, 0xffff0000, v121
	v_pk_fma_f32 v[44:45], v[20:21], v[48:49], v[114:115]
	v_pk_fma_f32 v[148:149], v[30:31], v[106:107], 1.0 op_sel_hi:[1,1,0]
	v_lshlrev_b32_e32 v106, 16, v105
	v_and_b32_e32 v107, 0xffff0000, v105
	v_pk_add_f32 v[50:51], v[50:51], v[54:55] neg_lo:[0,1] neg_hi:[0,1]
	v_pk_mul_f32 v[120:121], v[44:45], v[124:125]
	v_pk_add_f32 v[46:47], v[46:47], v[106:107] neg_lo:[0,1] neg_hi:[0,1]
	v_pk_fma_f32 v[50:51], v[22:23], v[50:51], v[54:55]
	v_pk_mul_f32 v[126:127], v[24:25], v[44:45]
	v_pk_mul_f32 v[44:45], v[122:123], v[120:121]
	v_pk_fma_f32 v[46:47], v[18:19], v[46:47], v[106:107]
	v_pk_mul_f32 v[48:49], v[50:51], v[148:149]
	v_pk_mul_f32 v[124:125], v[26:27], v[50:51]
	v_pk_mul_f32 v[50:51], v[126:127], v[126:127]
	v_fma_f32 v44, v32, v44, 0
	v_pk_mul_f32 v[104:105], v[46:47], v[48:49]
	v_pk_mul_f32 v[148:149], v[124:125], v[124:125]
	v_add_f32_e32 v50, v50, v51
	v_fmac_f32_e32 v44, v33, v45
	v_add_f32_e32 v45, v50, v148
	v_fmac_f32_e32 v44, v34, v104
	v_add_f32_e32 v45, v149, v45
	v_fmac_f32_e32 v44, v35, v105
	v_ashrrev_i32_e32 v103, 31, v102
	v_add_f32_dpp v45, v45, v45 quad_perm:[1,0,3,2] row_mask:0xf bank_mask:0xf bound_ctrl:1
	v_add_f32_dpp v44, v44, v44 quad_perm:[1,0,3,2] row_mask:0xf bank_mask:0xf bound_ctrl:1
	s_nop 0
	v_add_f32_dpp v45, v45, v45 quad_perm:[2,3,0,1] row_mask:0xf bank_mask:0xf bound_ctrl:1
	v_add_f32_dpp v44, v44, v44 quad_perm:[2,3,0,1] row_mask:0xf bank_mask:0xf bound_ctrl:1
	s_nop 0
	v_add_f32_dpp v58, v45, v45 row_half_mirror row_mask:0xf bank_mask:0xf bound_ctrl:1
	v_add_f32_dpp v44, v44, v44 row_half_mirror row_mask:0xf bank_mask:0xf bound_ctrl:1
	s_nop 0
	v_mov_b32_dpp v148, v58 row_mirror row_mask:0xf bank_mask:0xf bound_ctrl:1
	v_mov_b32_dpp v45, v44 row_mirror row_mask:0xf bank_mask:0xf bound_ctrl:1
	s_and_saveexec_b64 s[10:11], s[6:7]
	s_cbranch_execz .LBB0_197
	v_lshlrev_b64 v[50:51], 6, v[102:103]
	v_lshl_add_u64 v[50:51], v[98:99], 0, v[50:51]
	v_add_f32_e32 v44, v44, v45
	global_store_dword v[50:51], v44, off
.LBB0_197:
	s_or_b64 exec, exec, s[10:11]
	v_lshlrev_b32_e32 v50, 16, v52
	v_add_f32_e32 v50, v8, v50
	v_mul_f32_e32 v50, 0xbfb8aa3b, v50
	v_exp_f32_e32 v103, v50
	s_waitcnt vmcnt(8)
	v_lshlrev_b32_e32 v104, 16, v108
	v_and_b32_e32 v105, 0xffff0000, v108
	v_lshlrev_b32_e32 v44, 16, v109
	v_add_f32_e32 v103, 1.0, v103
	v_rcp_f32_e32 v103, v103
	v_and_b32_e32 v45, 0xffff0000, v109
	s_waitcnt vmcnt(8)
	v_lshlrev_b32_e32 v108, 16, v116
	v_and_b32_e32 v109, 0xffff0000, v116
	v_pk_add_f32 v[40:41], v[40:41], v[108:109] neg_lo:[0,1] neg_hi:[0,1]
	v_and_b32_e32 v116, 0xffff0000, v52
	v_pk_fma_f32 v[40:41], v[4:5], v[40:41], v[108:109]
	v_lshlrev_b32_e32 v50, 16, v117
	v_and_b32_e32 v51, 0xffff0000, v117
	v_lshlrev_b32_e32 v117, 16, v53
	v_and_b32_e32 v149, 0xffff0000, v53
	v_mul_f32_e32 v52, 0xbf1b4598, v103
	v_mul_f32_e32 v53, 0xbfb8aa3b, v40
	v_add_f32_e32 v103, v9, v116
	v_exp_f32_e32 v53, v53
	v_mul_f32_e32 v103, 0xbfb8aa3b, v103
	v_exp_f32_e32 v103, v103
	v_add_f32_e32 v117, v10, v117
	v_add_f32_e32 v53, 1.0, v53
	v_rcp_f32_e32 v116, v53
	v_add_f32_e32 v53, 1.0, v103
	v_mul_f32_e32 v103, 0xbfb8aa3b, v41
	v_exp_f32_e32 v103, v103
	v_mul_f32_e32 v117, 0xbfb8aa3b, v117
	v_exp_f32_e32 v150, v117
	v_rcp_f32_e32 v53, v53
	v_add_f32_e32 v103, 1.0, v103
	v_rcp_f32_e32 v117, v103
	v_add_f32_e32 v103, 1.0, v150
	v_rcp_f32_e32 v103, v103
	v_mul_f32_e32 v53, 0xbf1b4598, v53
	v_pk_mul_f32 v[40:41], v[40:41], v[116:117]
	v_add_f32_e32 v116, v11, v149
	v_mul_f32_e32 v116, 0xbfb8aa3b, v116
	v_exp_f32_e32 v116, v116
	v_mul_f32_e32 v52, 0x3fb8aa3b, v52
	v_mul_f32_e32 v53, 0x3fb8aa3b, v53
	v_exp_f32_e32 v52, v52
	v_add_f32_e32 v116, 1.0, v116
	v_rcp_f32_e32 v116, v116
	v_exp_f32_e32 v53, v53
	v_mul_f32_e32 v103, 0xbf1b4598, v103
	v_pk_add_f32 v[42:43], v[42:43], v[50:51] neg_lo:[0,1] neg_hi:[0,1]
	v_mul_f32_e32 v103, 0x3fb8aa3b, v103
	v_pk_fma_f32 v[42:43], v[6:7], v[42:43], v[50:51]
	v_add_f32_e32 v58, v58, v148
	v_exp_f32_e32 v150, v103
	v_mul_f32_e32 v103, 0xbfb8aa3b, v42
	v_mul_f32_e32 v116, 0xbf1b4598, v116
	v_max_f32_e32 v58, 0x179abe15, v58
	v_exp_f32_e32 v103, v103
	v_mul_f32_e32 v116, 0x3fb8aa3b, v116
	v_rsq_f32_e32 v58, v58
	v_pk_add_f32 v[52:53], v[52:53], -1.0 op_sel_hi:[1,0]
	v_exp_f32_e32 v151, v116
	v_pk_add_f32 v[116:117], v[52:53], 1.0 op_sel_hi:[1,0]
	v_add_f32_e32 v103, 1.0, v103
	v_rcp_f32_e32 v52, v116
	v_rcp_f32_e32 v53, v117
	v_pk_mul_f32 v[126:127], v[126:127], v[58:59] op_sel_hi:[1,0]
	v_rcp_f32_e32 v152, v103
	v_mul_f32_e32 v103, 0xbfb8aa3b, v43
	v_pk_mul_f32 v[112:113], v[112:113], v[126:127]
	v_exp_f32_e32 v103, v103
	v_pk_mul_f32 v[148:149], v[52:53], v[112:113]
	v_pk_add_f32 v[112:113], v[150:151], -1.0 op_sel_hi:[1,0]
	v_pk_add_f32 v[36:37], v[36:37], v[104:105] neg_lo:[0,1] neg_hi:[0,1]
	v_pk_add_f32 v[112:113], v[112:113], 1.0 op_sel_hi:[1,0]
	v_add_f32_e32 v103, 1.0, v103
	v_rcp_f32_e32 v150, v112
	v_rcp_f32_e32 v151, v113
	v_pk_add_f32 v[38:39], v[38:39], v[44:45] neg_lo:[0,1] neg_hi:[0,1]
	v_rcp_f32_e32 v153, v103
	v_pk_mul_f32 v[122:123], v[122:123], v[116:117]
	v_pk_mul_f32 v[52:53], v[52:53], v[120:121]
	v_pk_mul_f32 v[120:121], v[124:125], v[58:59] op_sel_hi:[1,0]
	v_pk_mul_f32 v[46:47], v[46:47], v[112:113]
	v_mad_i64_i32 v[124:125], s[10:11], v102, s23, v[56:57]
	v_pk_fma_f32 v[36:37], v[0:1], v[36:37], v[104:105]
	v_pk_fma_f32 v[38:39], v[2:3], v[38:39], v[44:45]
	v_pk_mul_f32 v[48:49], v[150:151], v[48:49]
	v_cvt_pk_bf16_f32 v122, v122, v123
	v_cvt_pk_bf16_f32 v123, v46, v47
	v_lshlrev_b64 v[46:47], 1, v[124:125]
	v_pk_mul_f32 v[110:111], v[110:111], v[120:121]
	v_lshl_add_u64 v[124:125], s[74:75], 0, v[46:47]
	v_cvt_pk_bf16_f32 v52, v52, v53
	v_cvt_pk_bf16_f32 v53, v48, v49
	v_lshl_add_u64 v[48:49], s[76:77], 0, v[46:47]
	v_cvt_pk_bf16_f32 v36, v36, v37
	v_cvt_pk_bf16_f32 v37, v38, v39
	v_lshl_add_u64 v[38:39], s[78:79], 0, v[46:47]
	v_pk_mul_f32 v[110:111], v[110:111], v[150:151]
	global_store_dwordx2 v[124:125], v[122:123], off
	global_store_dwordx2 v[48:49], v[52:53], off
	global_store_dwordx2 v[38:39], v[36:37], off
	v_cvt_pk_bf16_f32 v36, v126, v127
	v_cvt_pk_bf16_f32 v37, v120, v121
	v_lshl_add_u64 v[38:39], s[80:81], 0, v[46:47]
	v_pk_mul_f32 v[42:43], v[42:43], v[152:153]
	global_store_dwordx2 v[38:39], v[36:37], off
	v_cvt_pk_bf16_f32 v36, v148, v149
	v_cvt_pk_bf16_f32 v37, v110, v111
	v_lshl_add_u64 v[38:39], s[82:83], 0, v[46:47]
	global_store_dwordx2 v[38:39], v[36:37], off
	v_cvt_pk_bf16_f32 v36, v40, v41
	v_cvt_pk_bf16_f32 v37, v42, v43
	v_lshl_add_u64 v[38:39], s[84:85], 0, v[46:47]
	v_add_u32_e32 v120, 1, v102
	global_store_dwordx2 v[38:39], v[36:37], off
	v_mad_i64_i32 v[36:37], s[10:11], v120, s22, v[60:61]
	v_add_co_u32_e32 v36, vcc, s2, v36
	v_ashrrev_i32_e32 v121, 31, v120
	s_nop 0
	v_addc_co_u32_e32 v37, vcc, 0, v37, vcc
	s_waitcnt vmcnt(10)
	v_mov_b64_e32 v[40:41], v[246:247]
	v_mov_b64_e32 v[46:47], v[248:249]
	v_mov_b64_e32 v[42:43], v[250:251]
	v_mov_b64_e32 v[48:49], v[254:255]
	v_add_u32_e32 v242, 3, v102
	v_mad_i64_i32 v[242:243], s[26:27], v242, s22, v[60:61]
	global_load_dwordx2 v[246:247], v[242:243], off
	global_load_dwordx2 v[248:249], v[242:243], off offset:2048
	v_add_co_u32_e32 v244, vcc, s2, v242
	s_nop 1
	v_addc_co_u32_e32 v245, vcc, 0, v243, vcc
	global_load_dwordx2 v[250:251], v[244:245], off
	global_load_dwordx2 v[254:255], v[244:245], off offset:2048
	ds_read2st64_b64 v[36:39], v167 offset0:16 offset1:80
	s_waitcnt lgkmcnt(0)
	v_lshlrev_b32_e32 v58, 16, v38
	v_and_b32_e32 v38, 0xffff0000, v38
	v_add_f32_e32 v38, v13, v38
	v_mul_f32_e32 v38, 0xbfb8aa3b, v38
	v_lshlrev_b32_e32 v103, 16, v39
	v_and_b32_e32 v126, 0xffff0000, v39
	v_add_f32_e32 v39, v12, v58
	v_exp_f32_e32 v58, v38
	v_mul_f32_e32 v39, 0xbfb8aa3b, v39
	v_exp_f32_e32 v39, v39
	v_add_f32_e32 v58, 1.0, v58
	v_rcp_f32_e32 v123, v58
	v_add_f32_e32 v58, v14, v103
	v_mul_f32_e32 v58, 0xbfb8aa3b, v58
	v_add_f32_e32 v103, v15, v126
	v_add_f32_e32 v38, 1.0, v39
	v_exp_f32_e32 v58, v58
	v_mul_f32_e32 v103, 0xbfb8aa3b, v103
	v_rcp_f32_e32 v122, v38
	v_exp_f32_e32 v103, v103
	v_add_f32_e32 v58, 1.0, v58
	v_rcp_f32_e32 v126, v58
	v_add_f32_e32 v58, 1.0, v103
	v_rcp_f32_e32 v127, v58
	v_lshlrev_b32_e32 v52, 16, v40
	v_and_b32_e32 v53, 0xffff0000, v40
	v_lshlrev_b32_e32 v110, 16, v46
	v_and_b32_e32 v111, 0xffff0000, v46
	v_pk_add_f32 v[38:39], v[118:119], v[52:53] neg_lo:[0,1] neg_hi:[0,1]
	v_pk_add_f32 v[114:115], v[114:115], v[110:111] neg_lo:[0,1] neg_hi:[0,1]
	v_pk_add_f32 v[118:119], v[122:123], -1.0 op_sel_hi:[1,0]
	v_pk_fma_f32 v[114:115], v[20:21], v[114:115], v[110:111]
	v_pk_fma_f32 v[118:119], v[28:29], v[118:119], 1.0 op_sel_hi:[1,1,0]
	v_pk_fma_f32 v[38:39], v[16:17], v[38:39], v[52:53]
	v_pk_mul_f32 v[118:119], v[114:115], v[118:119]
	v_lshlrev_b32_e32 v40, 16, v41
	v_and_b32_e32 v41, 0xffff0000, v41
	v_lshlrev_b32_e32 v46, 16, v47
	v_and_b32_e32 v47, 0xffff0000, v47
	v_pk_mul_f32 v[124:125], v[38:39], v[118:119]
	v_pk_add_f32 v[106:107], v[106:107], v[40:41] neg_lo:[0,1] neg_hi:[0,1]
	v_fma_f32 v154, v32, v124, 0
	v_pk_add_f32 v[54:55], v[54:55], v[46:47] neg_lo:[0,1] neg_hi:[0,1]
	v_pk_mul_f32 v[148:149], v[24:25], v[114:115]
	v_fmac_f32_e32 v154, v33, v125
	v_pk_fma_f32 v[124:125], v[18:19], v[106:107], v[40:41]
	v_pk_fma_f32 v[54:55], v[22:23], v[54:55], v[46:47]
	v_pk_add_f32 v[106:107], v[126:127], -1.0 op_sel_hi:[1,0]
	v_pk_mul_f32 v[114:115], v[148:149], v[148:149]
	v_pk_fma_f32 v[106:107], v[30:31], v[106:107], 1.0 op_sel_hi:[1,1,0]
	v_pk_mul_f32 v[152:153], v[26:27], v[54:55]
	v_pk_mul_f32 v[150:151], v[54:55], v[106:107]
	v_pk_mul_f32 v[54:55], v[152:153], v[152:153]
	v_add_f32_e32 v58, v114, v115
	v_add_f32_e32 v54, v58, v54
	v_pk_mul_f32 v[106:107], v[124:125], v[150:151]
	v_add_f32_e32 v54, v55, v54
	v_fmac_f32_e32 v154, v34, v106
	v_fmac_f32_e32 v154, v35, v107
	v_add_f32_dpp v54, v54, v54 quad_perm:[1,0,3,2] row_mask:0xf bank_mask:0xf bound_ctrl:1
	s_nop 1
	v_add_f32_dpp v54, v54, v54 quad_perm:[2,3,0,1] row_mask:0xf bank_mask:0xf bound_ctrl:1
	s_nop 1
	v_add_f32_dpp v58, v54, v54 row_half_mirror row_mask:0xf bank_mask:0xf bound_ctrl:1
	v_add_f32_dpp v54, v154, v154 quad_perm:[1,0,3,2] row_mask:0xf bank_mask:0xf bound_ctrl:1
	s_nop 0
	v_mov_b32_dpp v103, v58 row_mirror row_mask:0xf bank_mask:0xf bound_ctrl:1
	v_add_f32_dpp v54, v54, v54 quad_perm:[2,3,0,1] row_mask:0xf bank_mask:0xf bound_ctrl:1
	s_nop 1
	v_add_f32_dpp v54, v54, v54 row_half_mirror row_mask:0xf bank_mask:0xf bound_ctrl:1
	s_nop 1
	v_mov_b32_dpp v55, v54 row_mirror row_mask:0xf bank_mask:0xf bound_ctrl:1
	s_and_saveexec_b64 s[10:11], s[6:7]
	s_cbranch_execz .LBB0_199
	v_lshlrev_b64 v[106:107], 6, v[120:121]
	v_lshl_add_u64 v[106:107], v[98:99], 0, v[106:107]
	v_add_f32_e32 v54, v54, v55
	global_store_dword v[106:107], v54, off
.LBB0_199:
	s_or_b64 exec, exec, s[10:11]
	v_lshlrev_b32_e32 v107, 16, v36
	v_add_f32_e32 v107, v8, v107
	v_mul_f32_e32 v107, 0xbfb8aa3b, v107
	v_exp_f32_e32 v114, v107
	v_lshlrev_b32_e32 v106, 16, v48
	v_and_b32_e32 v107, 0xffff0000, v48
	v_pk_add_f32 v[108:109], v[108:109], v[106:107] neg_lo:[0,1] neg_hi:[0,1]
	v_add_f32_e32 v114, 1.0, v114
	v_rcp_f32_e32 v114, v114
	v_and_b32_e32 v115, 0xffff0000, v36
	v_pk_fma_f32 v[108:109], v[4:5], v[108:109], v[106:107]
	v_lshlrev_b32_e32 v121, 16, v37
	v_and_b32_e32 v155, 0xffff0000, v37
	v_mul_f32_e32 v36, 0xbf1b4598, v114
	v_mul_f32_e32 v37, 0xbfb8aa3b, v108
	v_add_f32_e32 v114, v9, v115
	v_exp_f32_e32 v37, v37
	v_mul_f32_e32 v114, 0xbfb8aa3b, v114
	v_exp_f32_e32 v115, v114
	v_add_f32_e32 v121, v10, v121
	v_add_f32_e32 v37, 1.0, v37
	v_rcp_f32_e32 v114, v37
	v_add_f32_e32 v37, 1.0, v115
	v_mul_f32_e32 v115, 0xbfb8aa3b, v109
	v_mul_f32_e32 v121, 0xbfb8aa3b, v121
	v_exp_f32_e32 v115, v115
	v_exp_f32_e32 v121, v121
	v_lshlrev_b32_e32 v48, 16, v49
	v_and_b32_e32 v49, 0xffff0000, v49
	v_add_f32_e32 v115, 1.0, v115
	v_add_f32_e32 v121, 1.0, v121
	v_rcp_f32_e32 v115, v115
	v_rcp_f32_e32 v121, v121
	v_rcp_f32_e32 v37, v37
	v_pk_add_f32 v[50:51], v[50:51], v[48:49] neg_lo:[0,1] neg_hi:[0,1]
	v_pk_mul_f32 v[108:109], v[108:109], v[114:115]
	v_mul_f32_e32 v114, 0xbf1b4598, v121
	v_add_f32_e32 v115, v11, v155
	v_mul_f32_e32 v114, 0x3fb8aa3b, v114
	v_pk_fma_f32 v[50:51], v[6:7], v[50:51], v[48:49]
	v_mul_f32_e32 v115, 0xbfb8aa3b, v115
	v_exp_f32_e32 v154, v114
	v_mul_f32_e32 v114, 0xbfb8aa3b, v50
	v_exp_f32_e32 v115, v115
	v_mul_f32_e32 v121, 0xbfb8aa3b, v51
	v_exp_f32_e32 v114, v114
	v_exp_f32_e32 v121, v121
	v_mul_f32_e32 v37, 0xbf1b4598, v37
	v_mul_f32_e32 v36, 0x3fb8aa3b, v36
	v_mul_f32_e32 v37, 0x3fb8aa3b, v37
	v_exp_f32_e32 v36, v36
	v_exp_f32_e32 v37, v37
	v_add_f32_e32 v115, 1.0, v115
	v_add_f32_e32 v114, 1.0, v114
	v_rcp_f32_e32 v155, v115
	v_add_f32_e32 v115, 1.0, v121
	v_rcp_f32_e32 v114, v114
	v_rcp_f32_e32 v115, v115
	v_add_f32_e32 v58, v58, v103
	v_max_f32_e32 v58, 0x179abe15, v58
	v_pk_add_f32 v[36:37], v[36:37], -1.0 op_sel_hi:[1,0]
	v_mul_f32_e32 v121, 0xbf1b4598, v155
	v_rsq_f32_e32 v58, v58
	v_pk_add_f32 v[36:37], v[36:37], 1.0 op_sel_hi:[1,0]
	v_mul_f32_e32 v121, 0x3fb8aa3b, v121
	v_pk_mul_f32 v[50:51], v[50:51], v[114:115]
	v_pk_mul_f32 v[114:115], v[116:117], v[36:37]
	v_exp_f32_e32 v155, v121
	v_rcp_f32_e32 v36, v114
	v_rcp_f32_e32 v37, v115
	v_pk_mul_f32 v[148:149], v[148:149], v[58:59] op_sel_hi:[1,0]
	v_mad_i64_i32 v[120:121], s[10:11], v120, s23, v[56:57]
	v_pk_mul_f32 v[178:179], v[116:117], v[148:149]
	v_pk_mul_f32 v[116:117], v[122:123], v[148:149]
	v_pk_mul_f32 v[148:149], v[152:153], v[58:59] op_sel_hi:[1,0]
	v_pk_mul_f32 v[122:123], v[116:117], v[36:37]
	v_pk_add_f32 v[116:117], v[154:155], -1.0 op_sel_hi:[1,0]
	v_pk_mul_f32 v[36:37], v[118:119], v[36:37]
	v_pk_add_f32 v[116:117], v[116:117], 1.0 op_sel_hi:[1,0]
	v_lshlrev_b32_e32 v54, 16, v42
	v_pk_mul_f32 v[116:117], v[112:113], v[116:117]
	v_and_b32_e32 v55, 0xffff0000, v42
	v_rcp_f32_e32 v118, v116
	v_rcp_f32_e32 v119, v117
	v_lshlrev_b32_e32 v42, 16, v43
	v_and_b32_e32 v43, 0xffff0000, v43
	v_pk_mul_f32 v[38:39], v[38:39], v[114:115]
	v_pk_mul_f32 v[126:127], v[126:127], v[148:149]
	v_pk_mul_f32 v[124:125], v[124:125], v[116:117]
	v_lshlrev_b64 v[120:121], 1, v[120:121]
	v_pk_add_f32 v[104:105], v[104:105], v[54:55] neg_lo:[0,1] neg_hi:[0,1]
	v_pk_add_f32 v[44:45], v[44:45], v[42:43] neg_lo:[0,1] neg_hi:[0,1]
	v_pk_mul_f32 v[126:127], v[126:127], v[118:119]
	v_pk_mul_f32 v[118:119], v[150:151], v[118:119]
	v_cvt_pk_bf16_f32 v38, v38, v39
	v_cvt_pk_bf16_f32 v39, v124, v125
	v_lshl_add_u64 v[124:125], s[74:75], 0, v[120:121]
	v_pk_fma_f32 v[104:105], v[0:1], v[104:105], v[54:55]
	v_pk_fma_f32 v[44:45], v[2:3], v[44:45], v[42:43]
	global_store_dwordx2 v[124:125], v[38:39], off
	v_cvt_pk_bf16_f32 v36, v36, v37
	v_cvt_pk_bf16_f32 v37, v118, v119
	v_lshl_add_u64 v[38:39], s[76:77], 0, v[120:121]
	v_pk_mul_f32 v[112:113], v[112:113], v[148:149]
	global_store_dwordx2 v[38:39], v[36:37], off
	v_cvt_pk_bf16_f32 v36, v104, v105
	v_cvt_pk_bf16_f32 v37, v44, v45
	v_lshl_add_u64 v[38:39], s[78:79], 0, v[120:121]
	global_store_dwordx2 v[38:39], v[36:37], off
	v_cvt_pk_bf16_f32 v36, v178, v179
	v_cvt_pk_bf16_f32 v37, v112, v113
	v_lshl_add_u64 v[38:39], s[80:81], 0, v[120:121]
	global_store_dwordx2 v[38:39], v[36:37], off
	v_cvt_pk_bf16_f32 v36, v122, v123
	v_cvt_pk_bf16_f32 v37, v126, v127
	v_lshl_add_u64 v[38:39], s[82:83], 0, v[120:121]
	global_store_dwordx2 v[38:39], v[36:37], off
	v_cvt_pk_bf16_f32 v36, v108, v109
	v_cvt_pk_bf16_f32 v37, v50, v51
	v_lshl_add_u64 v[38:39], s[84:85], 0, v[120:121]
	v_add_u32_e32 v122, 2, v102
	global_store_dwordx2 v[38:39], v[36:37], off
	v_mad_i64_i32 v[36:37], s[10:11], v122, s22, v[60:61]
	v_add_co_u32_e32 v36, vcc, s2, v36
	v_ashrrev_i32_e32 v123, 31, v122
	s_nop 0
	v_addc_co_u32_e32 v37, vcc, 0, v37, vcc
	s_waitcnt vmcnt(16)
	v_mov_b64_e32 v[44:45], v[234:235]
	v_mov_b64_e32 v[50:51], v[236:237]
	v_mov_b64_e32 v[154:155], v[238:239]
	v_mov_b64_e32 v[118:119], v[240:241]
	v_add_u32_e32 v242, 4, v102
	v_mad_i64_i32 v[242:243], s[26:27], v242, s22, v[60:61]
	global_load_dwordx2 v[234:235], v[242:243], off
	global_load_dwordx2 v[236:237], v[242:243], off offset:2048
	v_add_co_u32_e32 v244, vcc, s2, v242
	s_nop 1
	v_addc_co_u32_e32 v245, vcc, 0, v243, vcc
	global_load_dwordx2 v[238:239], v[244:245], off
	global_load_dwordx2 v[240:241], v[244:245], off offset:2048
	ds_read2st64_b64 v[36:39], v168 offset0:16 offset1:80
	s_waitcnt lgkmcnt(0)
	v_lshlrev_b32_e32 v58, 16, v38
	v_and_b32_e32 v38, 0xffff0000, v38
	v_lshlrev_b32_e32 v103, 16, v39
	v_and_b32_e32 v126, 0xffff0000, v39
	v_add_f32_e32 v39, v12, v58
	v_mul_f32_e32 v39, 0xbfb8aa3b, v39
	v_add_f32_e32 v38, v13, v38
	v_exp_f32_e32 v39, v39
	v_mul_f32_e32 v38, 0xbfb8aa3b, v38
	v_exp_f32_e32 v58, v38
	v_add_f32_e32 v38, 1.0, v39
	v_rcp_f32_e32 v120, v38
	v_lshlrev_b32_e32 v108, 16, v44
	v_and_b32_e32 v109, 0xffff0000, v44
	v_pk_add_f32 v[38:39], v[52:53], v[108:109] neg_lo:[0,1] neg_hi:[0,1]
	v_add_f32_e32 v52, 1.0, v58
	v_add_f32_e32 v58, v14, v103
	v_mul_f32_e32 v58, 0xbfb8aa3b, v58
	v_add_f32_e32 v103, v15, v126
	v_exp_f32_e32 v58, v58
	v_mul_f32_e32 v103, 0xbfb8aa3b, v103
	v_exp_f32_e32 v103, v103
	v_rcp_f32_e32 v121, v52
	v_add_f32_e32 v58, 1.0, v58
	v_rcp_f32_e32 v148, v58
	v_add_f32_e32 v58, 1.0, v103
	v_rcp_f32_e32 v149, v58
	v_lshlrev_b32_e32 v44, 16, v45
	v_and_b32_e32 v45, 0xffff0000, v45
	v_lshlrev_b32_e32 v112, 16, v50
	v_and_b32_e32 v113, 0xffff0000, v50
	v_lshlrev_b32_e32 v50, 16, v51
	v_and_b32_e32 v51, 0xffff0000, v51
	v_pk_add_f32 v[52:53], v[110:111], v[112:113] neg_lo:[0,1] neg_hi:[0,1]
	v_pk_add_f32 v[40:41], v[40:41], v[44:45] neg_lo:[0,1] neg_hi:[0,1]
	v_pk_fma_f32 v[52:53], v[20:21], v[52:53], v[112:113]
	v_pk_add_f32 v[104:105], v[120:121], -1.0 op_sel_hi:[1,0]
	v_pk_fma_f32 v[126:127], v[18:19], v[40:41], v[44:45]
	v_pk_add_f32 v[40:41], v[46:47], v[50:51] neg_lo:[0,1] neg_hi:[0,1]
	v_pk_fma_f32 v[104:105], v[28:29], v[104:105], 1.0 op_sel_hi:[1,1,0]
	v_pk_mul_f32 v[150:151], v[24:25], v[52:53]
	v_pk_fma_f32 v[40:41], v[22:23], v[40:41], v[50:51]
	v_pk_add_f32 v[46:47], v[148:149], -1.0 op_sel_hi:[1,0]
	v_pk_fma_f32 v[38:39], v[16:17], v[38:39], v[108:109]
	v_pk_mul_f32 v[124:125], v[52:53], v[104:105]
	v_pk_mul_f32 v[52:53], v[150:151], v[150:151]
	v_pk_fma_f32 v[46:47], v[30:31], v[46:47], 1.0 op_sel_hi:[1,1,0]
	v_pk_mul_f32 v[152:153], v[26:27], v[40:41]
	v_pk_mul_f32 v[104:105], v[38:39], v[124:125]
	v_pk_mul_f32 v[46:47], v[40:41], v[46:47]
	v_pk_mul_f32 v[40:41], v[152:153], v[152:153]
	v_add_f32_e32 v52, v52, v53
	v_fma_f32 v110, v32, v104, 0
	v_add_f32_e32 v40, v52, v40
	v_fmac_f32_e32 v110, v33, v105
	v_pk_mul_f32 v[104:105], v[126:127], v[46:47]
	v_add_f32_e32 v40, v41, v40
	v_fmac_f32_e32 v110, v34, v104
	v_fmac_f32_e32 v110, v35, v105
	v_add_f32_dpp v40, v40, v40 quad_perm:[1,0,3,2] row_mask:0xf bank_mask:0xf bound_ctrl:1
	s_nop 1
	v_add_f32_dpp v40, v40, v40 quad_perm:[2,3,0,1] row_mask:0xf bank_mask:0xf bound_ctrl:1
	s_nop 1
	v_add_f32_dpp v58, v40, v40 row_half_mirror row_mask:0xf bank_mask:0xf bound_ctrl:1
	v_add_f32_dpp v40, v110, v110 quad_perm:[1,0,3,2] row_mask:0xf bank_mask:0xf bound_ctrl:1
	s_nop 0
	v_mov_b32_dpp v103, v58 row_mirror row_mask:0xf bank_mask:0xf bound_ctrl:1
	v_add_f32_dpp v40, v40, v40 quad_perm:[2,3,0,1] row_mask:0xf bank_mask:0xf bound_ctrl:1
	s_nop 1
	v_add_f32_dpp v40, v40, v40 row_half_mirror row_mask:0xf bank_mask:0xf bound_ctrl:1
	s_nop 1
	v_mov_b32_dpp v41, v40 row_mirror row_mask:0xf bank_mask:0xf bound_ctrl:1
	s_and_saveexec_b64 s[10:11], s[6:7]
	s_cbranch_execz .LBB0_201
	v_lshlrev_b64 v[52:53], 6, v[122:123]
	v_lshl_add_u64 v[52:53], v[98:99], 0, v[52:53]
	v_add_f32_e32 v40, v40, v41
	global_store_dword v[52:53], v40, off
.LBB0_201:
	s_or_b64 exec, exec, s[10:11]
	v_lshlrev_b32_e32 v52, 16, v36
	v_add_f32_e32 v52, v8, v52
	v_mul_f32_e32 v52, 0xbfb8aa3b, v52
	v_exp_f32_e32 v123, v52
	v_lshlrev_b32_e32 v110, 16, v118
	v_and_b32_e32 v111, 0xffff0000, v118
	v_pk_add_f32 v[106:107], v[106:107], v[110:111] neg_lo:[0,1] neg_hi:[0,1]
	v_add_f32_e32 v118, 1.0, v123
	v_rcp_f32_e32 v118, v118
	v_lshlrev_b32_e32 v52, 16, v119
	v_and_b32_e32 v53, 0xffff0000, v119
	v_and_b32_e32 v119, 0xffff0000, v36
	v_pk_fma_f32 v[106:107], v[4:5], v[106:107], v[110:111]
	v_lshlrev_b32_e32 v40, 16, v155
	v_and_b32_e32 v41, 0xffff0000, v155
	v_lshlrev_b32_e32 v123, 16, v37
	v_and_b32_e32 v155, 0xffff0000, v37
	v_mul_f32_e32 v36, 0xbf1b4598, v118
	v_mul_f32_e32 v37, 0xbfb8aa3b, v106
	v_add_f32_e32 v118, v9, v119
	v_exp_f32_e32 v37, v37
	v_mul_f32_e32 v118, 0xbfb8aa3b, v118
	v_exp_f32_e32 v119, v118
	v_add_f32_e32 v123, v10, v123
	v_add_f32_e32 v37, 1.0, v37
	v_rcp_f32_e32 v118, v37
	v_add_f32_e32 v37, 1.0, v119
	v_mul_f32_e32 v119, 0xbfb8aa3b, v107
	v_mul_f32_e32 v123, 0xbfb8aa3b, v123
	v_exp_f32_e32 v119, v119
	v_exp_f32_e32 v123, v123
	v_rcp_f32_e32 v37, v37
	v_pk_add_f32 v[48:49], v[48:49], v[52:53] neg_lo:[0,1] neg_hi:[0,1]
	v_add_f32_e32 v119, 1.0, v119
	v_add_f32_e32 v123, 1.0, v123
	v_rcp_f32_e32 v119, v119
	v_rcp_f32_e32 v123, v123
	v_pk_fma_f32 v[48:49], v[6:7], v[48:49], v[52:53]
	v_lshlrev_b32_e32 v104, 16, v154
	v_pk_mul_f32 v[106:107], v[106:107], v[118:119]
	v_mul_f32_e32 v118, 0xbf1b4598, v123
	v_add_f32_e32 v119, v11, v155
	v_mul_f32_e32 v118, 0x3fb8aa3b, v118
	v_mul_f32_e32 v119, 0xbfb8aa3b, v119
	v_and_b32_e32 v105, 0xffff0000, v154
	v_exp_f32_e32 v154, v118
	v_mul_f32_e32 v118, 0xbfb8aa3b, v48
	v_exp_f32_e32 v119, v119
	v_mul_f32_e32 v123, 0xbfb8aa3b, v49
	v_exp_f32_e32 v118, v118
	v_exp_f32_e32 v123, v123
	v_mul_f32_e32 v37, 0xbf1b4598, v37
	v_mul_f32_e32 v36, 0x3fb8aa3b, v36
	v_mul_f32_e32 v37, 0x3fb8aa3b, v37
	v_exp_f32_e32 v36, v36
	v_exp_f32_e32 v37, v37
	v_add_f32_e32 v119, 1.0, v119
	v_add_f32_e32 v118, 1.0, v118
	v_rcp_f32_e32 v155, v119
	v_add_f32_e32 v119, 1.0, v123
	v_rcp_f32_e32 v118, v118
	v_rcp_f32_e32 v119, v119
	v_add_f32_e32 v58, v58, v103
	v_max_f32_e32 v58, 0x179abe15, v58
	v_pk_add_f32 v[36:37], v[36:37], -1.0 op_sel_hi:[1,0]
	v_mul_f32_e32 v123, 0xbf1b4598, v155
	v_rsq_f32_e32 v58, v58
	v_pk_add_f32 v[36:37], v[36:37], 1.0 op_sel_hi:[1,0]
	v_mul_f32_e32 v123, 0x3fb8aa3b, v123
	v_pk_mul_f32 v[48:49], v[48:49], v[118:119]
	v_pk_mul_f32 v[118:119], v[114:115], v[36:37]
	v_exp_f32_e32 v155, v123
	v_rcp_f32_e32 v36, v118
	v_rcp_f32_e32 v37, v119
	v_pk_mul_f32 v[150:151], v[150:151], v[58:59] op_sel_hi:[1,0]
	v_pk_mul_f32 v[152:153], v[152:153], v[58:59] op_sel_hi:[1,0]
	v_pk_mul_f32 v[120:121], v[120:121], v[150:151]
	v_pk_mul_f32 v[114:115], v[114:115], v[150:151]
	v_pk_mul_f32 v[150:151], v[120:121], v[36:37]
	v_pk_add_f32 v[120:121], v[154:155], -1.0 op_sel_hi:[1,0]
	v_pk_mul_f32 v[36:37], v[124:125], v[36:37]
	v_pk_add_f32 v[120:121], v[120:121], 1.0 op_sel_hi:[1,0]
	v_mad_i64_i32 v[122:123], s[10:11], v122, s23, v[56:57]
	v_pk_mul_f32 v[120:121], v[116:117], v[120:121]
	v_pk_mul_f32 v[38:39], v[38:39], v[118:119]
	v_rcp_f32_e32 v124, v120
	v_rcp_f32_e32 v125, v121
	v_pk_mul_f32 v[148:149], v[148:149], v[152:153]
	v_pk_mul_f32 v[126:127], v[126:127], v[120:121]
	v_lshlrev_b64 v[122:123], 1, v[122:123]
	v_pk_add_f32 v[54:55], v[54:55], v[104:105] neg_lo:[0,1] neg_hi:[0,1]
	v_pk_add_f32 v[42:43], v[42:43], v[40:41] neg_lo:[0,1] neg_hi:[0,1]
	v_pk_mul_f32 v[148:149], v[148:149], v[124:125]
	v_pk_mul_f32 v[46:47], v[46:47], v[124:125]
	v_cvt_pk_bf16_f32 v38, v38, v39
	v_cvt_pk_bf16_f32 v39, v126, v127
	v_lshl_add_u64 v[124:125], s[74:75], 0, v[122:123]
	v_pk_fma_f32 v[54:55], v[0:1], v[54:55], v[104:105]
	v_pk_fma_f32 v[42:43], v[2:3], v[42:43], v[40:41]
	global_store_dwordx2 v[124:125], v[38:39], off
	v_cvt_pk_bf16_f32 v36, v36, v37
	v_cvt_pk_bf16_f32 v37, v46, v47
	v_lshl_add_u64 v[38:39], s[76:77], 0, v[122:123]
	v_pk_mul_f32 v[116:117], v[116:117], v[152:153]
	global_store_dwordx2 v[38:39], v[36:37], off
	v_cvt_pk_bf16_f32 v36, v54, v55
	v_cvt_pk_bf16_f32 v37, v42, v43
	v_lshl_add_u64 v[38:39], s[78:79], 0, v[122:123]
	global_store_dwordx2 v[38:39], v[36:37], off
	v_cvt_pk_bf16_f32 v36, v114, v115
	v_cvt_pk_bf16_f32 v37, v116, v117
	v_lshl_add_u64 v[38:39], s[80:81], 0, v[122:123]
	global_store_dwordx2 v[38:39], v[36:37], off
	v_cvt_pk_bf16_f32 v36, v150, v151
	v_cvt_pk_bf16_f32 v37, v148, v149
	v_lshl_add_u64 v[38:39], s[82:83], 0, v[122:123]
	global_store_dwordx2 v[38:39], v[36:37], off
	v_cvt_pk_bf16_f32 v36, v106, v107
	v_cvt_pk_bf16_f32 v37, v48, v49
	v_lshl_add_u64 v[38:39], s[84:85], 0, v[122:123]
	v_add_u32_e32 v122, 3, v102
	global_store_dwordx2 v[38:39], v[36:37], off
	v_mad_i64_i32 v[36:37], s[10:11], v122, s22, v[60:61]
	v_add_co_u32_e32 v36, vcc, s2, v36
	v_ashrrev_i32_e32 v123, 31, v122
	s_nop 0
	v_addc_co_u32_e32 v37, vcc, 0, v37, vcc
	s_waitcnt vmcnt(16)
	v_mov_b64_e32 v[46:47], v[246:247]
	v_mov_b64_e32 v[48:49], v[248:249]
	v_mov_b64_e32 v[42:43], v[250:251]
	v_mov_b64_e32 v[116:117], v[254:255]
	v_add_u32_e32 v242, 5, v102
	v_mad_i64_i32 v[242:243], s[26:27], v242, s22, v[60:61]
	global_load_dwordx2 v[246:247], v[242:243], off
	global_load_dwordx2 v[248:249], v[242:243], off offset:2048
	v_add_co_u32_e32 v244, vcc, s2, v242
	s_nop 1
	v_addc_co_u32_e32 v245, vcc, 0, v243, vcc
	global_load_dwordx2 v[250:251], v[244:245], off
	global_load_dwordx2 v[254:255], v[244:245], off offset:2048
	ds_read2st64_b64 v[36:39], v169 offset0:16 offset1:80
	s_waitcnt lgkmcnt(0)
	v_lshlrev_b32_e32 v54, 16, v38
	v_and_b32_e32 v38, 0xffff0000, v38
	v_lshlrev_b32_e32 v58, 16, v39
	v_and_b32_e32 v103, 0xffff0000, v39
	v_add_f32_e32 v39, v12, v54
	v_add_f32_e32 v38, v13, v38
	v_mul_f32_e32 v39, 0xbfb8aa3b, v39
	v_mul_f32_e32 v38, 0xbfb8aa3b, v38
	v_exp_f32_e32 v39, v39
	v_exp_f32_e32 v54, v38
	v_add_f32_e32 v58, v14, v58
	v_mul_f32_e32 v58, 0xbfb8aa3b, v58
	v_add_f32_e32 v103, v15, v103
	v_add_f32_e32 v38, 1.0, v39
	v_add_f32_e32 v54, 1.0, v54
	v_exp_f32_e32 v58, v58
	v_mul_f32_e32 v103, 0xbfb8aa3b, v103
	v_rcp_f32_e32 v124, v38
	v_rcp_f32_e32 v125, v54
	v_exp_f32_e32 v103, v103
	v_add_f32_e32 v58, 1.0, v58
	v_rcp_f32_e32 v126, v58
	v_add_f32_e32 v58, 1.0, v103
	v_rcp_f32_e32 v127, v58
	v_lshlrev_b32_e32 v106, 16, v46
	v_and_b32_e32 v107, 0xffff0000, v46
	v_lshlrev_b32_e32 v114, 16, v48
	v_and_b32_e32 v115, 0xffff0000, v48
	v_pk_add_f32 v[38:39], v[108:109], v[106:107] neg_lo:[0,1] neg_hi:[0,1]
	v_pk_add_f32 v[54:55], v[112:113], v[114:115] neg_lo:[0,1] neg_hi:[0,1]
	v_pk_add_f32 v[108:109], v[124:125], -1.0 op_sel_hi:[1,0]
	v_pk_fma_f32 v[54:55], v[20:21], v[54:55], v[114:115]
	v_pk_fma_f32 v[108:109], v[28:29], v[108:109], 1.0 op_sel_hi:[1,1,0]
	v_pk_fma_f32 v[38:39], v[16:17], v[38:39], v[106:107]
	v_pk_mul_f32 v[108:109], v[54:55], v[108:109]
	v_lshlrev_b32_e32 v48, 16, v49
	v_and_b32_e32 v49, 0xffff0000, v49
	v_pk_mul_f32 v[112:113], v[38:39], v[108:109]
	v_pk_add_f32 v[50:51], v[50:51], v[48:49] neg_lo:[0,1] neg_hi:[0,1]
	v_fma_f32 v154, v32, v112, 0
	v_pk_mul_f32 v[148:149], v[24:25], v[54:55]
	v_fmac_f32_e32 v154, v33, v113
	v_pk_fma_f32 v[50:51], v[22:23], v[50:51], v[48:49]
	v_pk_add_f32 v[112:113], v[126:127], -1.0 op_sel_hi:[1,0]
	v_lshlrev_b32_e32 v46, 16, v47
	v_and_b32_e32 v47, 0xffff0000, v47
	v_pk_mul_f32 v[54:55], v[148:149], v[148:149]
	v_pk_fma_f32 v[112:113], v[30:31], v[112:113], 1.0 op_sel_hi:[1,1,0]
	v_pk_mul_f32 v[152:153], v[26:27], v[50:51]
	v_pk_add_f32 v[44:45], v[44:45], v[46:47] neg_lo:[0,1] neg_hi:[0,1]
	v_pk_mul_f32 v[150:151], v[50:51], v[112:113]
	v_pk_mul_f32 v[50:51], v[152:153], v[152:153]
	v_add_f32_e32 v54, v54, v55
	v_pk_fma_f32 v[44:45], v[18:19], v[44:45], v[46:47]
	v_add_f32_e32 v50, v54, v50
	v_pk_mul_f32 v[112:113], v[44:45], v[150:151]
	v_add_f32_e32 v50, v51, v50
	v_fmac_f32_e32 v154, v34, v112
	v_fmac_f32_e32 v154, v35, v113
	v_add_f32_dpp v50, v50, v50 quad_perm:[1,0,3,2] row_mask:0xf bank_mask:0xf bound_ctrl:1
	s_nop 1
	v_add_f32_dpp v50, v50, v50 quad_perm:[2,3,0,1] row_mask:0xf bank_mask:0xf bound_ctrl:1
	s_nop 1
	v_add_f32_dpp v58, v50, v50 row_half_mirror row_mask:0xf bank_mask:0xf bound_ctrl:1
	v_add_f32_dpp v50, v154, v154 quad_perm:[1,0,3,2] row_mask:0xf bank_mask:0xf bound_ctrl:1
	s_nop 0
	v_mov_b32_dpp v103, v58 row_mirror row_mask:0xf bank_mask:0xf bound_ctrl:1
	v_add_f32_dpp v50, v50, v50 quad_perm:[2,3,0,1] row_mask:0xf bank_mask:0xf bound_ctrl:1
	s_nop 1
	v_add_f32_dpp v50, v50, v50 row_half_mirror row_mask:0xf bank_mask:0xf bound_ctrl:1
	s_nop 1
	v_mov_b32_dpp v51, v50 row_mirror row_mask:0xf bank_mask:0xf bound_ctrl:1
	s_and_saveexec_b64 s[10:11], s[6:7]
	s_cbranch_execz .LBB0_203
	v_lshlrev_b64 v[54:55], 6, v[122:123]
	v_lshl_add_u64 v[54:55], v[98:99], 0, v[54:55]
	v_add_f32_e32 v50, v50, v51
	global_store_dword v[54:55], v50, off
.LBB0_203:
	s_or_b64 exec, exec, s[10:11]
	v_lshlrev_b32_e32 v50, 16, v36
	v_add_f32_e32 v50, v8, v50
	v_mul_f32_e32 v50, 0xbfb8aa3b, v50
	v_exp_f32_e32 v123, v50
	v_lshlrev_b32_e32 v112, 16, v116
	v_and_b32_e32 v113, 0xffff0000, v116
	v_pk_add_f32 v[110:111], v[110:111], v[112:113] neg_lo:[0,1] neg_hi:[0,1]
	v_add_f32_e32 v116, 1.0, v123
	v_rcp_f32_e32 v116, v116
	v_lshlrev_b32_e32 v50, 16, v117
	v_and_b32_e32 v51, 0xffff0000, v117
	v_and_b32_e32 v117, 0xffff0000, v36
	v_pk_fma_f32 v[110:111], v[4:5], v[110:111], v[112:113]
	v_lshlrev_b32_e32 v123, 16, v37
	v_and_b32_e32 v155, 0xffff0000, v37
	v_mul_f32_e32 v36, 0xbf1b4598, v116
	v_mul_f32_e32 v37, 0xbfb8aa3b, v110
	v_add_f32_e32 v116, v9, v117
	v_exp_f32_e32 v37, v37
	v_mul_f32_e32 v116, 0xbfb8aa3b, v116
	v_exp_f32_e32 v117, v116
	v_add_f32_e32 v123, v10, v123
	v_add_f32_e32 v37, 1.0, v37
	v_rcp_f32_e32 v116, v37
	v_add_f32_e32 v37, 1.0, v117
	v_mul_f32_e32 v117, 0xbfb8aa3b, v111
	v_mul_f32_e32 v123, 0xbfb8aa3b, v123
	v_exp_f32_e32 v117, v117
	v_exp_f32_e32 v123, v123
	v_rcp_f32_e32 v37, v37
	v_pk_add_f32 v[52:53], v[52:53], v[50:51] neg_lo:[0,1] neg_hi:[0,1]
	v_add_f32_e32 v117, 1.0, v117
	v_add_f32_e32 v123, 1.0, v123
	v_rcp_f32_e32 v117, v117
	v_rcp_f32_e32 v123, v123
	v_pk_fma_f32 v[52:53], v[6:7], v[52:53], v[50:51]
	v_mul_f32_e32 v37, 0xbf1b4598, v37
	v_pk_mul_f32 v[110:111], v[110:111], v[116:117]
	v_mul_f32_e32 v116, 0xbf1b4598, v123
	v_add_f32_e32 v117, v11, v155
	v_mul_f32_e32 v116, 0x3fb8aa3b, v116
	v_mul_f32_e32 v117, 0xbfb8aa3b, v117
	v_exp_f32_e32 v154, v116
	v_mul_f32_e32 v116, 0xbfb8aa3b, v52
	v_exp_f32_e32 v117, v117
	v_mul_f32_e32 v123, 0xbfb8aa3b, v53
	v_exp_f32_e32 v116, v116
	v_exp_f32_e32 v123, v123
	v_mul_f32_e32 v36, 0x3fb8aa3b, v36
	v_mul_f32_e32 v37, 0x3fb8aa3b, v37
	v_exp_f32_e32 v36, v36
	v_exp_f32_e32 v37, v37
	v_add_f32_e32 v117, 1.0, v117
	v_add_f32_e32 v116, 1.0, v116
	v_rcp_f32_e32 v155, v117
	v_add_f32_e32 v117, 1.0, v123
	v_rcp_f32_e32 v116, v116
	v_rcp_f32_e32 v117, v117
	v_add_f32_e32 v58, v58, v103
	v_max_f32_e32 v58, 0x179abe15, v58
	v_pk_add_f32 v[36:37], v[36:37], -1.0 op_sel_hi:[1,0]
	v_mul_f32_e32 v123, 0xbf1b4598, v155
	v_rsq_f32_e32 v58, v58
	v_pk_add_f32 v[36:37], v[36:37], 1.0 op_sel_hi:[1,0]
	v_mul_f32_e32 v123, 0x3fb8aa3b, v123
	v_pk_mul_f32 v[52:53], v[52:53], v[116:117]
	v_pk_mul_f32 v[116:117], v[118:119], v[36:37]
	v_exp_f32_e32 v155, v123
	v_rcp_f32_e32 v36, v116
	v_rcp_f32_e32 v37, v117
	v_pk_mul_f32 v[148:149], v[148:149], v[58:59] op_sel_hi:[1,0]
	v_pk_mul_f32 v[38:39], v[38:39], v[116:117]
	v_pk_mul_f32 v[178:179], v[118:119], v[148:149]
	v_pk_mul_f32 v[118:119], v[124:125], v[148:149]
	v_pk_mul_f32 v[148:149], v[152:153], v[58:59] op_sel_hi:[1,0]
	v_pk_mul_f32 v[124:125], v[118:119], v[36:37]
	v_pk_mul_f32 v[36:37], v[108:109], v[36:37]
	v_pk_add_f32 v[108:109], v[154:155], -1.0 op_sel_hi:[1,0]
	v_mad_i64_i32 v[122:123], s[10:11], v122, s23, v[56:57]
	v_pk_add_f32 v[108:109], v[108:109], 1.0 op_sel_hi:[1,0]
	v_lshlrev_b32_e32 v54, 16, v42
	v_pk_mul_f32 v[118:119], v[120:121], v[108:109]
	v_and_b32_e32 v55, 0xffff0000, v42
	v_rcp_f32_e32 v108, v118
	v_rcp_f32_e32 v109, v119
	v_pk_mul_f32 v[44:45], v[44:45], v[118:119]
	v_lshlrev_b32_e32 v42, 16, v43
	v_and_b32_e32 v43, 0xffff0000, v43
	v_pk_mul_f32 v[126:127], v[126:127], v[148:149]
	v_cvt_pk_bf16_f32 v38, v38, v39
	v_cvt_pk_bf16_f32 v39, v44, v45
	v_lshlrev_b64 v[44:45], 1, v[122:123]
	v_pk_add_f32 v[104:105], v[104:105], v[54:55] neg_lo:[0,1] neg_hi:[0,1]
	v_pk_add_f32 v[40:41], v[40:41], v[42:43] neg_lo:[0,1] neg_hi:[0,1]
	v_pk_mul_f32 v[126:127], v[126:127], v[108:109]
	v_pk_mul_f32 v[108:109], v[150:151], v[108:109]
	v_lshl_add_u64 v[122:123], s[74:75], 0, v[44:45]
	v_pk_fma_f32 v[104:105], v[0:1], v[104:105], v[54:55]
	v_pk_fma_f32 v[40:41], v[2:3], v[40:41], v[42:43]
	global_store_dwordx2 v[122:123], v[38:39], off
	v_cvt_pk_bf16_f32 v36, v36, v37
	v_cvt_pk_bf16_f32 v37, v108, v109
	v_lshl_add_u64 v[38:39], s[76:77], 0, v[44:45]
	v_pk_mul_f32 v[120:121], v[120:121], v[148:149]
	global_store_dwordx2 v[38:39], v[36:37], off
	v_cvt_pk_bf16_f32 v36, v104, v105
	v_cvt_pk_bf16_f32 v37, v40, v41
	v_lshl_add_u64 v[38:39], s[78:79], 0, v[44:45]
	global_store_dwordx2 v[38:39], v[36:37], off
	v_cvt_pk_bf16_f32 v36, v178, v179
	v_cvt_pk_bf16_f32 v37, v120, v121
	v_lshl_add_u64 v[38:39], s[80:81], 0, v[44:45]
	global_store_dwordx2 v[38:39], v[36:37], off
	v_cvt_pk_bf16_f32 v36, v124, v125
	v_cvt_pk_bf16_f32 v37, v126, v127
	v_lshl_add_u64 v[38:39], s[82:83], 0, v[44:45]
	global_store_dwordx2 v[38:39], v[36:37], off
	v_cvt_pk_bf16_f32 v36, v110, v111
	v_cvt_pk_bf16_f32 v37, v52, v53
	v_lshl_add_u64 v[38:39], s[84:85], 0, v[44:45]
	v_add_u32_e32 v122, 4, v102
	global_store_dwordx2 v[38:39], v[36:37], off
	v_mad_i64_i32 v[36:37], s[10:11], v122, s22, v[60:61]
	v_add_co_u32_e32 v36, vcc, s2, v36
	v_ashrrev_i32_e32 v123, 31, v122
	s_nop 0
	v_addc_co_u32_e32 v37, vcc, 0, v37, vcc
	s_waitcnt vmcnt(16)
	v_mov_b64_e32 v[44:45], v[234:235]
	v_mov_b64_e32 v[52:53], v[236:237]
	v_mov_b64_e32 v[40:41], v[238:239]
	v_mov_b64_e32 v[120:121], v[240:241]
	v_add_u32_e32 v242, 6, v102
	v_mad_i64_i32 v[242:243], s[26:27], v242, s22, v[60:61]
	global_load_dwordx2 v[234:235], v[242:243], off
	global_load_dwordx2 v[236:237], v[242:243], off offset:2048
	v_add_co_u32_e32 v244, vcc, s2, v242
	s_nop 1
	v_addc_co_u32_e32 v245, vcc, 0, v243, vcc
	global_load_dwordx2 v[238:239], v[244:245], off
	global_load_dwordx2 v[240:241], v[244:245], off offset:2048
	ds_read2st64_b64 v[36:39], v170 offset0:16 offset1:80
	s_waitcnt lgkmcnt(0)
	v_lshlrev_b32_e32 v58, 16, v38
	v_and_b32_e32 v38, 0xffff0000, v38
	v_add_f32_e32 v38, v13, v38
	v_mul_f32_e32 v38, 0xbfb8aa3b, v38
	v_lshlrev_b32_e32 v103, 16, v39
	v_and_b32_e32 v126, 0xffff0000, v39
	v_add_f32_e32 v39, v12, v58
	v_exp_f32_e32 v58, v38
	v_mul_f32_e32 v39, 0xbfb8aa3b, v39
	v_exp_f32_e32 v39, v39
	v_add_f32_e32 v58, 1.0, v58
	v_rcp_f32_e32 v125, v58
	v_add_f32_e32 v58, v14, v103
	v_mul_f32_e32 v58, 0xbfb8aa3b, v58
	v_add_f32_e32 v103, v15, v126
	v_exp_f32_e32 v58, v58
	v_mul_f32_e32 v103, 0xbfb8aa3b, v103
	v_exp_f32_e32 v103, v103
	v_add_f32_e32 v38, 1.0, v39
	v_add_f32_e32 v58, 1.0, v58
	v_rcp_f32_e32 v124, v38
	v_rcp_f32_e32 v148, v58
	v_add_f32_e32 v58, 1.0, v103
	v_rcp_f32_e32 v149, v58
	v_lshlrev_b32_e32 v108, 16, v44
	v_and_b32_e32 v109, 0xffff0000, v44
	v_lshlrev_b32_e32 v44, 16, v45
	v_and_b32_e32 v45, 0xffff0000, v45
	v_lshlrev_b32_e32 v110, 16, v52
	v_and_b32_e32 v111, 0xffff0000, v52
	v_lshlrev_b32_e32 v52, 16, v53
	v_and_b32_e32 v53, 0xffff0000, v53
	v_pk_add_f32 v[104:105], v[114:115], v[110:111] neg_lo:[0,1] neg_hi:[0,1]
	v_pk_add_f32 v[46:47], v[46:47], v[44:45] neg_lo:[0,1] neg_hi:[0,1]
	v_pk_add_f32 v[38:39], v[106:107], v[108:109] neg_lo:[0,1] neg_hi:[0,1]
	v_pk_fma_f32 v[104:105], v[20:21], v[104:105], v[110:111]
	v_pk_add_f32 v[106:107], v[124:125], -1.0 op_sel_hi:[1,0]
	v_pk_fma_f32 v[126:127], v[18:19], v[46:47], v[44:45]
	v_pk_add_f32 v[46:47], v[48:49], v[52:53] neg_lo:[0,1] neg_hi:[0,1]
	v_pk_fma_f32 v[106:107], v[28:29], v[106:107], 1.0 op_sel_hi:[1,1,0]
	v_pk_mul_f32 v[150:151], v[24:25], v[104:105]
	v_pk_fma_f32 v[46:47], v[22:23], v[46:47], v[52:53]
	v_pk_add_f32 v[48:49], v[148:149], -1.0 op_sel_hi:[1,0]
	v_pk_fma_f32 v[38:39], v[16:17], v[38:39], v[108:109]
	v_pk_mul_f32 v[106:107], v[104:105], v[106:107]
	v_pk_mul_f32 v[104:105], v[150:151], v[150:151]
	v_pk_fma_f32 v[48:49], v[30:31], v[48:49], 1.0 op_sel_hi:[1,1,0]
	v_pk_mul_f32 v[152:153], v[26:27], v[46:47]
	v_pk_mul_f32 v[114:115], v[38:39], v[106:107]
	v_pk_mul_f32 v[48:49], v[46:47], v[48:49]
	v_pk_mul_f32 v[46:47], v[152:153], v[152:153]
	v_add_f32_e32 v58, v104, v105
	v_fma_f32 v154, v32, v114, 0
	v_add_f32_e32 v46, v58, v46
	v_fmac_f32_e32 v154, v33, v115
	v_pk_mul_f32 v[114:115], v[126:127], v[48:49]
	v_add_f32_e32 v46, v47, v46
	v_fmac_f32_e32 v154, v34, v114
	v_fmac_f32_e32 v154, v35, v115
	v_add_f32_dpp v46, v46, v46 quad_perm:[1,0,3,2] row_mask:0xf bank_mask:0xf bound_ctrl:1
	s_nop 1
	v_add_f32_dpp v46, v46, v46 quad_perm:[2,3,0,1] row_mask:0xf bank_mask:0xf bound_ctrl:1
	s_nop 1
	v_add_f32_dpp v58, v46, v46 row_half_mirror row_mask:0xf bank_mask:0xf bound_ctrl:1
	v_add_f32_dpp v46, v154, v154 quad_perm:[1,0,3,2] row_mask:0xf bank_mask:0xf bound_ctrl:1
	s_nop 0
	v_mov_b32_dpp v103, v58 row_mirror row_mask:0xf bank_mask:0xf bound_ctrl:1
	v_add_f32_dpp v46, v46, v46 quad_perm:[2,3,0,1] row_mask:0xf bank_mask:0xf bound_ctrl:1
	s_nop 1
	v_add_f32_dpp v46, v46, v46 row_half_mirror row_mask:0xf bank_mask:0xf bound_ctrl:1
	s_nop 1
	v_mov_b32_dpp v47, v46 row_mirror row_mask:0xf bank_mask:0xf bound_ctrl:1
	s_and_saveexec_b64 s[10:11], s[6:7]
	s_cbranch_execz .LBB0_205
	v_lshlrev_b64 v[104:105], 6, v[122:123]
	v_lshl_add_u64 v[104:105], v[98:99], 0, v[104:105]
	v_add_f32_e32 v46, v46, v47
	global_store_dword v[104:105], v46, off
.LBB0_205:
	s_or_b64 exec, exec, s[10:11]
	v_lshlrev_b32_e32 v46, 16, v36
	v_add_f32_e32 v46, v8, v46
	v_mul_f32_e32 v46, 0xbfb8aa3b, v46
	v_exp_f32_e32 v123, v46
	v_lshlrev_b32_e32 v114, 16, v120
	v_and_b32_e32 v115, 0xffff0000, v120
	v_pk_add_f32 v[112:113], v[112:113], v[114:115] neg_lo:[0,1] neg_hi:[0,1]
	v_add_f32_e32 v120, 1.0, v123
	v_rcp_f32_e32 v120, v120
	v_lshlrev_b32_e32 v46, 16, v121
	v_and_b32_e32 v47, 0xffff0000, v121
	v_and_b32_e32 v121, 0xffff0000, v36
	v_pk_fma_f32 v[112:113], v[4:5], v[112:113], v[114:115]
	v_lshlrev_b32_e32 v123, 16, v37
	v_and_b32_e32 v155, 0xffff0000, v37
	v_mul_f32_e32 v36, 0xbf1b4598, v120
	v_mul_f32_e32 v37, 0xbfb8aa3b, v112
	v_add_f32_e32 v120, v9, v121
	v_exp_f32_e32 v37, v37
	v_mul_f32_e32 v120, 0xbfb8aa3b, v120
	v_exp_f32_e32 v121, v120
	v_add_f32_e32 v123, v10, v123
	v_add_f32_e32 v37, 1.0, v37
	v_rcp_f32_e32 v120, v37
	v_add_f32_e32 v37, 1.0, v121
	v_mul_f32_e32 v121, 0xbfb8aa3b, v113
	v_mul_f32_e32 v123, 0xbfb8aa3b, v123
	v_exp_f32_e32 v121, v121
	v_exp_f32_e32 v123, v123
	v_rcp_f32_e32 v37, v37
	v_pk_add_f32 v[50:51], v[50:51], v[46:47] neg_lo:[0,1] neg_hi:[0,1]
	v_add_f32_e32 v121, 1.0, v121
	v_add_f32_e32 v123, 1.0, v123
	v_rcp_f32_e32 v121, v121
	v_rcp_f32_e32 v123, v123
	v_pk_fma_f32 v[50:51], v[6:7], v[50:51], v[46:47]
	v_mul_f32_e32 v37, 0xbf1b4598, v37
	v_pk_mul_f32 v[112:113], v[112:113], v[120:121]
	v_mul_f32_e32 v120, 0xbf1b4598, v123
	v_add_f32_e32 v121, v11, v155
	v_mul_f32_e32 v120, 0x3fb8aa3b, v120
	v_mul_f32_e32 v121, 0xbfb8aa3b, v121
	v_exp_f32_e32 v154, v120
	v_mul_f32_e32 v120, 0xbfb8aa3b, v50
	v_exp_f32_e32 v121, v121
	v_mul_f32_e32 v123, 0xbfb8aa3b, v51
	v_exp_f32_e32 v120, v120
	v_exp_f32_e32 v123, v123
	v_mul_f32_e32 v36, 0x3fb8aa3b, v36
	v_mul_f32_e32 v37, 0x3fb8aa3b, v37
	v_exp_f32_e32 v36, v36
	v_exp_f32_e32 v37, v37
	v_add_f32_e32 v121, 1.0, v121
	v_add_f32_e32 v120, 1.0, v120
	v_rcp_f32_e32 v155, v121
	v_add_f32_e32 v121, 1.0, v123
	v_rcp_f32_e32 v120, v120
	v_rcp_f32_e32 v121, v121
	v_add_f32_e32 v58, v58, v103
	v_max_f32_e32 v58, 0x179abe15, v58
	v_pk_add_f32 v[36:37], v[36:37], -1.0 op_sel_hi:[1,0]
	v_mul_f32_e32 v123, 0xbf1b4598, v155
	v_rsq_f32_e32 v58, v58
	v_pk_add_f32 v[36:37], v[36:37], 1.0 op_sel_hi:[1,0]
	v_mul_f32_e32 v123, 0x3fb8aa3b, v123
	v_pk_mul_f32 v[50:51], v[50:51], v[120:121]
	v_pk_mul_f32 v[120:121], v[116:117], v[36:37]
	v_exp_f32_e32 v155, v123
	v_rcp_f32_e32 v36, v120
	v_rcp_f32_e32 v37, v121
	v_pk_mul_f32 v[150:151], v[150:151], v[58:59] op_sel_hi:[1,0]
	v_lshlrev_b32_e32 v104, 16, v40
	v_pk_mul_f32 v[178:179], v[116:117], v[150:151]
	v_pk_mul_f32 v[116:117], v[124:125], v[150:151]
	v_pk_mul_f32 v[150:151], v[152:153], v[58:59] op_sel_hi:[1,0]
	v_pk_mul_f32 v[124:125], v[116:117], v[36:37]
	v_pk_mul_f32 v[36:37], v[106:107], v[36:37]
	v_pk_add_f32 v[106:107], v[154:155], -1.0 op_sel_hi:[1,0]
	v_pk_mul_f32 v[148:149], v[148:149], v[150:151]
	v_pk_add_f32 v[106:107], v[106:107], 1.0 op_sel_hi:[1,0]
	v_and_b32_e32 v105, 0xffff0000, v40
	v_pk_mul_f32 v[116:117], v[118:119], v[106:107]
	v_lshlrev_b32_e32 v40, 16, v41
	v_rcp_f32_e32 v106, v116
	v_rcp_f32_e32 v107, v117
	v_and_b32_e32 v41, 0xffff0000, v41
	v_pk_mul_f32 v[38:39], v[38:39], v[120:121]
	v_pk_mul_f32 v[126:127], v[126:127], v[116:117]
	v_pk_mul_f32 v[148:149], v[148:149], v[106:107]
	v_pk_mul_f32 v[48:49], v[48:49], v[106:107]
	v_mad_i64_i32 v[106:107], s[10:11], v122, s23, v[56:57]
	v_lshlrev_b64 v[106:107], 1, v[106:107]
	v_pk_add_f32 v[54:55], v[54:55], v[104:105] neg_lo:[0,1] neg_hi:[0,1]
	v_pk_add_f32 v[42:43], v[42:43], v[40:41] neg_lo:[0,1] neg_hi:[0,1]
	v_cvt_pk_bf16_f32 v38, v38, v39
	v_cvt_pk_bf16_f32 v39, v126, v127
	v_lshl_add_u64 v[122:123], s[74:75], 0, v[106:107]
	v_pk_fma_f32 v[54:55], v[0:1], v[54:55], v[104:105]
	v_pk_fma_f32 v[42:43], v[2:3], v[42:43], v[40:41]
	global_store_dwordx2 v[122:123], v[38:39], off
	v_cvt_pk_bf16_f32 v36, v36, v37
	v_cvt_pk_bf16_f32 v37, v48, v49
	v_lshl_add_u64 v[38:39], s[76:77], 0, v[106:107]
	v_pk_mul_f32 v[118:119], v[118:119], v[150:151]
	global_store_dwordx2 v[38:39], v[36:37], off
	v_cvt_pk_bf16_f32 v36, v54, v55
	v_cvt_pk_bf16_f32 v37, v42, v43
	v_lshl_add_u64 v[38:39], s[78:79], 0, v[106:107]
	global_store_dwordx2 v[38:39], v[36:37], off
	v_cvt_pk_bf16_f32 v36, v178, v179
	v_cvt_pk_bf16_f32 v37, v118, v119
	v_lshl_add_u64 v[38:39], s[80:81], 0, v[106:107]
	global_store_dwordx2 v[38:39], v[36:37], off
	v_cvt_pk_bf16_f32 v36, v124, v125
	v_cvt_pk_bf16_f32 v37, v148, v149
	v_lshl_add_u64 v[38:39], s[82:83], 0, v[106:107]
	global_store_dwordx2 v[38:39], v[36:37], off
	v_cvt_pk_bf16_f32 v36, v112, v113
	v_cvt_pk_bf16_f32 v37, v50, v51
	v_lshl_add_u64 v[38:39], s[84:85], 0, v[106:107]
	v_add_u32_e32 v122, 5, v102
	global_store_dwordx2 v[38:39], v[36:37], off
	v_mad_i64_i32 v[36:37], s[10:11], v122, s22, v[60:61]
	v_add_co_u32_e32 v36, vcc, s2, v36
	v_ashrrev_i32_e32 v123, 31, v122
	s_nop 0
	v_addc_co_u32_e32 v37, vcc, 0, v37, vcc
	s_waitcnt vmcnt(16)
	v_mov_b64_e32 v[48:49], v[246:247]
	v_mov_b64_e32 v[50:51], v[248:249]
	v_mov_b64_e32 v[42:43], v[250:251]
	v_mov_b64_e32 v[118:119], v[254:255]
	v_add_u32_e32 v242, 7, v102
	v_mad_i64_i32 v[242:243], s[26:27], v242, s22, v[60:61]
	global_load_dwordx2 v[246:247], v[242:243], off
	global_load_dwordx2 v[248:249], v[242:243], off offset:2048
	v_add_co_u32_e32 v244, vcc, s2, v242
	s_nop 1
	v_addc_co_u32_e32 v245, vcc, 0, v243, vcc
	global_load_dwordx2 v[250:251], v[244:245], off
	global_load_dwordx2 v[254:255], v[244:245], off offset:2048
	ds_read2st64_b64 v[36:39], v171 offset0:16 offset1:80
	s_waitcnt lgkmcnt(0)
	v_lshlrev_b32_e32 v54, 16, v38
	v_and_b32_e32 v38, 0xffff0000, v38
	v_lshlrev_b32_e32 v58, 16, v39
	v_and_b32_e32 v103, 0xffff0000, v39
	v_add_f32_e32 v39, v12, v54
	v_add_f32_e32 v38, v13, v38
	v_mul_f32_e32 v39, 0xbfb8aa3b, v39
	v_mul_f32_e32 v38, 0xbfb8aa3b, v38
	v_exp_f32_e32 v39, v39
	v_exp_f32_e32 v54, v38
	v_add_f32_e32 v58, v14, v58
	v_mul_f32_e32 v58, 0xbfb8aa3b, v58
	v_add_f32_e32 v103, v15, v103
	v_add_f32_e32 v38, 1.0, v39
	v_add_f32_e32 v54, 1.0, v54
	v_exp_f32_e32 v58, v58
	v_mul_f32_e32 v103, 0xbfb8aa3b, v103
	v_rcp_f32_e32 v124, v38
	v_rcp_f32_e32 v125, v54
	v_exp_f32_e32 v103, v103
	v_add_f32_e32 v58, 1.0, v58
	v_rcp_f32_e32 v126, v58
	v_add_f32_e32 v58, 1.0, v103
	v_rcp_f32_e32 v127, v58
	v_lshlrev_b32_e32 v106, 16, v48
	v_and_b32_e32 v107, 0xffff0000, v48
	v_lshlrev_b32_e32 v112, 16, v50
	v_and_b32_e32 v113, 0xffff0000, v50
	v_pk_add_f32 v[38:39], v[108:109], v[106:107] neg_lo:[0,1] neg_hi:[0,1]
	v_pk_add_f32 v[54:55], v[110:111], v[112:113] neg_lo:[0,1] neg_hi:[0,1]
	v_pk_add_f32 v[108:109], v[124:125], -1.0 op_sel_hi:[1,0]
	v_pk_fma_f32 v[54:55], v[20:21], v[54:55], v[112:113]
	v_pk_fma_f32 v[108:109], v[28:29], v[108:109], 1.0 op_sel_hi:[1,1,0]
	v_pk_fma_f32 v[38:39], v[16:17], v[38:39], v[106:107]
	v_pk_mul_f32 v[108:109], v[54:55], v[108:109]
	v_lshlrev_b32_e32 v50, 16, v51
	v_and_b32_e32 v51, 0xffff0000, v51
	v_pk_mul_f32 v[110:111], v[38:39], v[108:109]
	v_pk_add_f32 v[52:53], v[52:53], v[50:51] neg_lo:[0,1] neg_hi:[0,1]
	v_fma_f32 v154, v32, v110, 0
	v_pk_mul_f32 v[148:149], v[24:25], v[54:55]
	v_fmac_f32_e32 v154, v33, v111
	v_pk_fma_f32 v[52:53], v[22:23], v[52:53], v[50:51]
	v_pk_add_f32 v[110:111], v[126:127], -1.0 op_sel_hi:[1,0]
	v_lshlrev_b32_e32 v48, 16, v49
	v_and_b32_e32 v49, 0xffff0000, v49
	v_pk_mul_f32 v[54:55], v[148:149], v[148:149]
	v_pk_fma_f32 v[110:111], v[30:31], v[110:111], 1.0 op_sel_hi:[1,1,0]
	v_pk_mul_f32 v[152:153], v[26:27], v[52:53]
	v_pk_add_f32 v[44:45], v[44:45], v[48:49] neg_lo:[0,1] neg_hi:[0,1]
	v_pk_mul_f32 v[150:151], v[52:53], v[110:111]
	v_pk_mul_f32 v[52:53], v[152:153], v[152:153]
	v_add_f32_e32 v54, v54, v55
	v_pk_fma_f32 v[44:45], v[18:19], v[44:45], v[48:49]
	v_add_f32_e32 v52, v54, v52
	v_pk_mul_f32 v[110:111], v[44:45], v[150:151]
	v_add_f32_e32 v52, v53, v52
	v_fmac_f32_e32 v154, v34, v110
	v_fmac_f32_e32 v154, v35, v111
	v_add_f32_dpp v52, v52, v52 quad_perm:[1,0,3,2] row_mask:0xf bank_mask:0xf bound_ctrl:1
	s_nop 1
	v_add_f32_dpp v52, v52, v52 quad_perm:[2,3,0,1] row_mask:0xf bank_mask:0xf bound_ctrl:1
	s_nop 1
	v_add_f32_dpp v58, v52, v52 row_half_mirror row_mask:0xf bank_mask:0xf bound_ctrl:1
	v_add_f32_dpp v52, v154, v154 quad_perm:[1,0,3,2] row_mask:0xf bank_mask:0xf bound_ctrl:1
	s_nop 0
	v_mov_b32_dpp v103, v58 row_mirror row_mask:0xf bank_mask:0xf bound_ctrl:1
	v_add_f32_dpp v52, v52, v52 quad_perm:[2,3,0,1] row_mask:0xf bank_mask:0xf bound_ctrl:1
	s_nop 1
	v_add_f32_dpp v52, v52, v52 row_half_mirror row_mask:0xf bank_mask:0xf bound_ctrl:1
	s_nop 1
	v_mov_b32_dpp v53, v52 row_mirror row_mask:0xf bank_mask:0xf bound_ctrl:1
	s_and_saveexec_b64 s[10:11], s[6:7]
	s_cbranch_execz .LBB0_207
	v_lshlrev_b64 v[54:55], 6, v[122:123]
	v_lshl_add_u64 v[54:55], v[98:99], 0, v[54:55]
	v_add_f32_e32 v52, v52, v53
	global_store_dword v[54:55], v52, off
.LBB0_207:
	s_or_b64 exec, exec, s[10:11]
	v_lshlrev_b32_e32 v52, 16, v36
	v_add_f32_e32 v52, v8, v52
	v_mul_f32_e32 v52, 0xbfb8aa3b, v52
	v_exp_f32_e32 v123, v52
	v_lshlrev_b32_e32 v110, 16, v118
	v_and_b32_e32 v111, 0xffff0000, v118
	v_pk_add_f32 v[114:115], v[114:115], v[110:111] neg_lo:[0,1] neg_hi:[0,1]
	v_add_f32_e32 v118, 1.0, v123
	v_rcp_f32_e32 v118, v118
	v_lshlrev_b32_e32 v52, 16, v119
	v_and_b32_e32 v53, 0xffff0000, v119
	v_and_b32_e32 v119, 0xffff0000, v36
	v_pk_fma_f32 v[114:115], v[4:5], v[114:115], v[110:111]
	v_lshlrev_b32_e32 v123, 16, v37
	v_and_b32_e32 v155, 0xffff0000, v37
	v_mul_f32_e32 v36, 0xbf1b4598, v118
	v_mul_f32_e32 v37, 0xbfb8aa3b, v114
	v_add_f32_e32 v118, v9, v119
	v_exp_f32_e32 v37, v37
	v_mul_f32_e32 v118, 0xbfb8aa3b, v118
	v_exp_f32_e32 v119, v118
	v_add_f32_e32 v123, v10, v123
	v_add_f32_e32 v37, 1.0, v37
	v_rcp_f32_e32 v118, v37
	v_add_f32_e32 v37, 1.0, v119
	v_mul_f32_e32 v119, 0xbfb8aa3b, v115
	v_mul_f32_e32 v123, 0xbfb8aa3b, v123
	v_exp_f32_e32 v119, v119
	v_exp_f32_e32 v123, v123
	v_rcp_f32_e32 v37, v37
	v_pk_add_f32 v[46:47], v[46:47], v[52:53] neg_lo:[0,1] neg_hi:[0,1]
	v_add_f32_e32 v119, 1.0, v119
	v_add_f32_e32 v123, 1.0, v123
	v_rcp_f32_e32 v119, v119
	v_rcp_f32_e32 v123, v123
	v_pk_fma_f32 v[46:47], v[6:7], v[46:47], v[52:53]
	v_mul_f32_e32 v37, 0xbf1b4598, v37
	v_pk_mul_f32 v[114:115], v[114:115], v[118:119]
	v_mul_f32_e32 v118, 0xbf1b4598, v123
	v_add_f32_e32 v119, v11, v155
	v_mul_f32_e32 v118, 0x3fb8aa3b, v118
	v_mul_f32_e32 v119, 0xbfb8aa3b, v119
	v_exp_f32_e32 v154, v118
	v_mul_f32_e32 v118, 0xbfb8aa3b, v46
	v_exp_f32_e32 v119, v119
	v_mul_f32_e32 v123, 0xbfb8aa3b, v47
	v_exp_f32_e32 v118, v118
	v_exp_f32_e32 v123, v123
	v_mul_f32_e32 v36, 0x3fb8aa3b, v36
	v_mul_f32_e32 v37, 0x3fb8aa3b, v37
	v_exp_f32_e32 v36, v36
	v_exp_f32_e32 v37, v37
	v_add_f32_e32 v119, 1.0, v119
	v_add_f32_e32 v118, 1.0, v118
	v_rcp_f32_e32 v155, v119
	v_add_f32_e32 v119, 1.0, v123
	v_rcp_f32_e32 v118, v118
	v_rcp_f32_e32 v119, v119
	v_add_f32_e32 v58, v58, v103
	v_max_f32_e32 v58, 0x179abe15, v58
	v_pk_add_f32 v[36:37], v[36:37], -1.0 op_sel_hi:[1,0]
	v_mul_f32_e32 v123, 0xbf1b4598, v155
	v_rsq_f32_e32 v58, v58
	v_pk_add_f32 v[36:37], v[36:37], 1.0 op_sel_hi:[1,0]
	v_mul_f32_e32 v123, 0x3fb8aa3b, v123
	v_pk_mul_f32 v[46:47], v[46:47], v[118:119]
	v_pk_mul_f32 v[118:119], v[120:121], v[36:37]
	v_exp_f32_e32 v155, v123
	v_rcp_f32_e32 v36, v118
	v_rcp_f32_e32 v37, v119
	v_pk_mul_f32 v[148:149], v[148:149], v[58:59] op_sel_hi:[1,0]
	v_pk_mul_f32 v[38:39], v[38:39], v[118:119]
	v_pk_mul_f32 v[178:179], v[120:121], v[148:149]
	v_pk_mul_f32 v[120:121], v[124:125], v[148:149]
	v_pk_mul_f32 v[148:149], v[152:153], v[58:59] op_sel_hi:[1,0]
	v_pk_mul_f32 v[124:125], v[120:121], v[36:37]
	v_pk_mul_f32 v[36:37], v[108:109], v[36:37]
	v_pk_add_f32 v[108:109], v[154:155], -1.0 op_sel_hi:[1,0]
	v_mad_i64_i32 v[122:123], s[10:11], v122, s23, v[56:57]
	v_pk_add_f32 v[108:109], v[108:109], 1.0 op_sel_hi:[1,0]
	v_lshlrev_b32_e32 v54, 16, v42
	v_pk_mul_f32 v[120:121], v[116:117], v[108:109]
	v_and_b32_e32 v55, 0xffff0000, v42
	v_rcp_f32_e32 v108, v120
	v_rcp_f32_e32 v109, v121
	v_pk_mul_f32 v[44:45], v[44:45], v[120:121]
	v_lshlrev_b32_e32 v42, 16, v43
	v_and_b32_e32 v43, 0xffff0000, v43
	v_pk_mul_f32 v[126:127], v[126:127], v[148:149]
	v_cvt_pk_bf16_f32 v38, v38, v39
	v_cvt_pk_bf16_f32 v39, v44, v45
	v_lshlrev_b64 v[44:45], 1, v[122:123]
	v_pk_add_f32 v[104:105], v[104:105], v[54:55] neg_lo:[0,1] neg_hi:[0,1]
	v_pk_add_f32 v[40:41], v[40:41], v[42:43] neg_lo:[0,1] neg_hi:[0,1]
	v_pk_mul_f32 v[126:127], v[126:127], v[108:109]
	v_pk_mul_f32 v[108:109], v[150:151], v[108:109]
	v_lshl_add_u64 v[122:123], s[74:75], 0, v[44:45]
	v_pk_fma_f32 v[104:105], v[0:1], v[104:105], v[54:55]
	v_pk_fma_f32 v[40:41], v[2:3], v[40:41], v[42:43]
	global_store_dwordx2 v[122:123], v[38:39], off
	v_cvt_pk_bf16_f32 v36, v36, v37
	v_cvt_pk_bf16_f32 v37, v108, v109
	v_lshl_add_u64 v[38:39], s[76:77], 0, v[44:45]
	v_pk_mul_f32 v[116:117], v[116:117], v[148:149]
	global_store_dwordx2 v[38:39], v[36:37], off
	v_cvt_pk_bf16_f32 v36, v104, v105
	v_cvt_pk_bf16_f32 v37, v40, v41
	v_lshl_add_u64 v[38:39], s[78:79], 0, v[44:45]
	global_store_dwordx2 v[38:39], v[36:37], off
	v_cvt_pk_bf16_f32 v36, v178, v179
	v_cvt_pk_bf16_f32 v37, v116, v117
	v_lshl_add_u64 v[38:39], s[80:81], 0, v[44:45]
	global_store_dwordx2 v[38:39], v[36:37], off
	v_cvt_pk_bf16_f32 v36, v124, v125
	v_cvt_pk_bf16_f32 v37, v126, v127
	v_lshl_add_u64 v[38:39], s[82:83], 0, v[44:45]
	global_store_dwordx2 v[38:39], v[36:37], off
	v_cvt_pk_bf16_f32 v36, v114, v115
	v_cvt_pk_bf16_f32 v37, v46, v47
	v_lshl_add_u64 v[38:39], s[84:85], 0, v[44:45]
	v_add_u32_e32 v116, 6, v102
	global_store_dwordx2 v[38:39], v[36:37], off
	v_mad_i64_i32 v[36:37], s[10:11], v116, s22, v[60:61]
	v_add_co_u32_e32 v36, vcc, s2, v36
	v_ashrrev_i32_e32 v117, 31, v116
	s_nop 0
	v_addc_co_u32_e32 v37, vcc, 0, v37, vcc
	s_waitcnt vmcnt(16)
	v_mov_b64_e32 v[44:45], v[234:235]
	v_mov_b64_e32 v[46:47], v[236:237]
	v_mov_b64_e32 v[40:41], v[238:239]
	v_mov_b64_e32 v[152:153], v[240:241]
	ds_read2st64_b64 v[36:39], v172 offset0:16 offset1:80
	s_waitcnt lgkmcnt(0)
	v_lshlrev_b32_e32 v58, 16, v38
	v_and_b32_e32 v38, 0xffff0000, v38
	v_add_f32_e32 v38, v13, v38
	v_mul_f32_e32 v38, 0xbfb8aa3b, v38
	v_lshlrev_b32_e32 v103, 16, v39
	v_and_b32_e32 v124, 0xffff0000, v39
	v_add_f32_e32 v39, v12, v58
	v_exp_f32_e32 v58, v38
	v_mul_f32_e32 v39, 0xbfb8aa3b, v39
	v_exp_f32_e32 v39, v39
	v_add_f32_e32 v58, 1.0, v58
	v_rcp_f32_e32 v123, v58
	v_add_f32_e32 v58, v14, v103
	v_mul_f32_e32 v58, 0xbfb8aa3b, v58
	v_add_f32_e32 v103, v15, v124
	v_add_f32_e32 v38, 1.0, v39
	v_exp_f32_e32 v58, v58
	v_mul_f32_e32 v103, 0xbfb8aa3b, v103
	v_rcp_f32_e32 v122, v38
	v_exp_f32_e32 v103, v103
	v_add_f32_e32 v58, 1.0, v58
	v_rcp_f32_e32 v124, v58
	v_add_f32_e32 v58, 1.0, v103
	v_rcp_f32_e32 v125, v58
	v_lshlrev_b32_e32 v108, 16, v44
	v_and_b32_e32 v109, 0xffff0000, v44
	v_lshlrev_b32_e32 v114, 16, v46
	v_and_b32_e32 v115, 0xffff0000, v46
	v_pk_add_f32 v[38:39], v[106:107], v[108:109] neg_lo:[0,1] neg_hi:[0,1]
	v_pk_add_f32 v[104:105], v[112:113], v[114:115] neg_lo:[0,1] neg_hi:[0,1]
	v_pk_add_f32 v[106:107], v[122:123], -1.0 op_sel_hi:[1,0]
	v_pk_fma_f32 v[104:105], v[20:21], v[104:105], v[114:115]
	v_pk_fma_f32 v[106:107], v[28:29], v[106:107], 1.0 op_sel_hi:[1,1,0]
	v_pk_fma_f32 v[38:39], v[16:17], v[38:39], v[108:109]
	v_pk_mul_f32 v[106:107], v[104:105], v[106:107]
	v_lshlrev_b32_e32 v44, 16, v45
	v_and_b32_e32 v45, 0xffff0000, v45
	v_pk_mul_f32 v[112:113], v[38:39], v[106:107]
	v_lshlrev_b32_e32 v46, 16, v47
	v_and_b32_e32 v47, 0xffff0000, v47
	v_fma_f32 v154, v32, v112, 0
	v_pk_add_f32 v[48:49], v[48:49], v[44:45] neg_lo:[0,1] neg_hi:[0,1]
	v_fmac_f32_e32 v154, v33, v113
	v_pk_fma_f32 v[112:113], v[18:19], v[48:49], v[44:45]
	v_pk_add_f32 v[48:49], v[50:51], v[46:47] neg_lo:[0,1] neg_hi:[0,1]
	v_pk_add_f32 v[50:51], v[124:125], -1.0 op_sel_hi:[1,0]
	v_pk_fma_f32 v[48:49], v[22:23], v[48:49], v[46:47]
	v_pk_fma_f32 v[50:51], v[30:31], v[50:51], 1.0 op_sel_hi:[1,1,0]
	v_pk_mul_f32 v[126:127], v[24:25], v[104:105]
	v_pk_mul_f32 v[148:149], v[48:49], v[50:51]
	v_pk_mul_f32 v[104:105], v[126:127], v[126:127]
	v_pk_mul_f32 v[50:51], v[112:113], v[148:149]
	v_pk_mul_f32 v[150:151], v[26:27], v[48:49]
	v_fmac_f32_e32 v154, v34, v50
	v_pk_mul_f32 v[48:49], v[150:151], v[150:151]
	v_add_f32_e32 v50, v104, v105
	v_add_f32_e32 v48, v50, v48
	v_add_f32_e32 v48, v49, v48
	v_fmac_f32_e32 v154, v35, v51
	s_nop 0
	v_add_f32_dpp v48, v48, v48 quad_perm:[1,0,3,2] row_mask:0xf bank_mask:0xf bound_ctrl:1
	s_nop 1
	v_add_f32_dpp v48, v48, v48 quad_perm:[2,3,0,1] row_mask:0xf bank_mask:0xf bound_ctrl:1
	s_nop 1
	v_add_f32_dpp v58, v48, v48 row_half_mirror row_mask:0xf bank_mask:0xf bound_ctrl:1
	v_add_f32_dpp v48, v154, v154 quad_perm:[1,0,3,2] row_mask:0xf bank_mask:0xf bound_ctrl:1
	s_nop 0
	v_mov_b32_dpp v103, v58 row_mirror row_mask:0xf bank_mask:0xf bound_ctrl:1
	v_add_f32_dpp v48, v48, v48 quad_perm:[2,3,0,1] row_mask:0xf bank_mask:0xf bound_ctrl:1
	s_nop 1
	v_add_f32_dpp v48, v48, v48 row_half_mirror row_mask:0xf bank_mask:0xf bound_ctrl:1
	s_nop 1
	v_mov_b32_dpp v49, v48 row_mirror row_mask:0xf bank_mask:0xf bound_ctrl:1
	s_and_saveexec_b64 s[10:11], s[6:7]
	s_cbranch_execz .LBB0_209
	v_lshlrev_b64 v[50:51], 6, v[116:117]
	v_lshl_add_u64 v[50:51], v[98:99], 0, v[50:51]
	v_add_f32_e32 v48, v48, v49
	global_store_dword v[50:51], v48, off
.LBB0_209:
	s_or_b64 exec, exec, s[10:11]
	v_lshlrev_b32_e32 v48, 16, v36
	v_add_f32_e32 v48, v8, v48
	v_mul_f32_e32 v48, 0xbfb8aa3b, v48
	v_exp_f32_e32 v117, v48
	v_lshlrev_b32_e32 v104, 16, v152
	v_and_b32_e32 v105, 0xffff0000, v152
	v_pk_add_f32 v[110:111], v[110:111], v[104:105] neg_lo:[0,1] neg_hi:[0,1]
	v_add_f32_e32 v117, 1.0, v117
	v_rcp_f32_e32 v117, v117
	v_and_b32_e32 v152, 0xffff0000, v36
	v_pk_fma_f32 v[110:111], v[4:5], v[110:111], v[104:105]
	v_lshlrev_b32_e32 v48, 16, v153
	v_and_b32_e32 v49, 0xffff0000, v153
	v_lshlrev_b32_e32 v153, 16, v37
	v_and_b32_e32 v178, 0xffff0000, v37
	v_mul_f32_e32 v36, 0xbf1b4598, v117
	v_mul_f32_e32 v37, 0xbfb8aa3b, v110
	v_add_f32_e32 v117, v9, v152
	v_exp_f32_e32 v37, v37
	v_mul_f32_e32 v117, 0xbfb8aa3b, v117
	v_exp_f32_e32 v117, v117
	v_add_f32_e32 v153, v10, v153
	v_add_f32_e32 v37, 1.0, v37
	v_rcp_f32_e32 v152, v37
	v_add_f32_e32 v37, 1.0, v117
	v_mul_f32_e32 v117, 0xbfb8aa3b, v111
	v_exp_f32_e32 v117, v117
	v_mul_f32_e32 v153, 0xbfb8aa3b, v153
	v_exp_f32_e32 v154, v153
	v_lshlrev_b32_e32 v50, 16, v40
	v_add_f32_e32 v117, 1.0, v117
	v_rcp_f32_e32 v153, v117
	v_add_f32_e32 v117, 1.0, v154
	v_rcp_f32_e32 v117, v117
	v_and_b32_e32 v51, 0xffff0000, v40
	v_lshlrev_b32_e32 v40, 16, v41
	v_and_b32_e32 v41, 0xffff0000, v41
	v_pk_add_f32 v[42:43], v[42:43], v[40:41] neg_lo:[0,1] neg_hi:[0,1]
	v_mul_f32_e32 v117, 0xbf1b4598, v117
	v_pk_fma_f32 v[154:155], v[2:3], v[42:43], v[40:41]
	v_pk_add_f32 v[42:43], v[52:53], v[48:49] neg_lo:[0,1] neg_hi:[0,1]
	v_add_f32_e32 v53, v11, v178
	v_mul_f32_e32 v117, 0x3fb8aa3b, v117
	v_pk_fma_f32 v[42:43], v[6:7], v[42:43], v[48:49]
	v_mul_f32_e32 v53, 0xbfb8aa3b, v53
	v_pk_mul_f32 v[110:111], v[110:111], v[152:153]
	v_exp_f32_e32 v152, v117
	v_mul_f32_e32 v52, 0xbfb8aa3b, v42
	v_exp_f32_e32 v53, v53
	v_mul_f32_e32 v117, 0xbfb8aa3b, v43
	v_rcp_f32_e32 v37, v37
	v_exp_f32_e32 v52, v52
	v_exp_f32_e32 v117, v117
	v_add_f32_e32 v53, 1.0, v53
	v_mul_f32_e32 v37, 0xbf1b4598, v37
	v_add_f32_e32 v52, 1.0, v52
	v_rcp_f32_e32 v153, v53
	v_add_f32_e32 v53, 1.0, v117
	v_mul_f32_e32 v36, 0x3fb8aa3b, v36
	v_mul_f32_e32 v37, 0x3fb8aa3b, v37
	v_rcp_f32_e32 v52, v52
	v_rcp_f32_e32 v53, v53
	v_exp_f32_e32 v36, v36
	v_exp_f32_e32 v37, v37
	v_mul_f32_e32 v117, 0xbf1b4598, v153
	v_pk_mul_f32 v[178:179], v[42:43], v[52:53]
	v_add_f32_e32 v42, v58, v103
	v_max_f32_e32 v42, 0x179abe15, v42
	v_pk_add_f32 v[36:37], v[36:37], -1.0 op_sel_hi:[1,0]
	v_rsq_f32_e32 v58, v42
	v_pk_add_f32 v[36:37], v[36:37], 1.0 op_sel_hi:[1,0]
	v_mul_f32_e32 v117, 0x3fb8aa3b, v117
	v_pk_mul_f32 v[42:43], v[118:119], v[36:37]
	v_exp_f32_e32 v153, v117
	v_rcp_f32_e32 v36, v42
	v_rcp_f32_e32 v37, v43
	v_pk_mul_f32 v[52:53], v[126:127], v[58:59] op_sel_hi:[1,0]
	v_pk_mul_f32 v[38:39], v[38:39], v[42:43]
	v_pk_mul_f32 v[118:119], v[118:119], v[52:53]
	v_pk_mul_f32 v[52:53], v[122:123], v[52:53]
	v_pk_mul_f32 v[126:127], v[150:151], v[58:59] op_sel_hi:[1,0]
	v_pk_mul_f32 v[122:123], v[52:53], v[36:37]
	v_pk_add_f32 v[52:53], v[152:153], -1.0 op_sel_hi:[1,0]
	v_pk_mul_f32 v[36:37], v[106:107], v[36:37]
	v_pk_add_f32 v[52:53], v[52:53], 1.0 op_sel_hi:[1,0]
	v_mad_i64_i32 v[116:117], s[10:11], v116, s23, v[56:57]
	v_pk_mul_f32 v[52:53], v[120:121], v[52:53]
	v_pk_mul_f32 v[124:125], v[124:125], v[126:127]
	v_rcp_f32_e32 v106, v52
	v_rcp_f32_e32 v107, v53
	v_pk_mul_f32 v[112:113], v[112:113], v[52:53]
	v_cvt_pk_bf16_f32 v38, v38, v39
	v_cvt_pk_bf16_f32 v39, v112, v113
	v_lshlrev_b64 v[112:113], 1, v[116:117]
	v_pk_add_f32 v[54:55], v[54:55], v[50:51] neg_lo:[0,1] neg_hi:[0,1]
	v_pk_mul_f32 v[124:125], v[124:125], v[106:107]
	v_pk_mul_f32 v[106:107], v[148:149], v[106:107]
	v_lshl_add_u64 v[116:117], s[74:75], 0, v[112:113]
	v_pk_fma_f32 v[54:55], v[0:1], v[54:55], v[50:51]
	global_store_dwordx2 v[116:117], v[38:39], off
	v_cvt_pk_bf16_f32 v36, v36, v37
	v_cvt_pk_bf16_f32 v37, v106, v107
	v_lshl_add_u64 v[38:39], s[76:77], 0, v[112:113]
	v_pk_mul_f32 v[120:121], v[120:121], v[126:127]
	global_store_dwordx2 v[38:39], v[36:37], off
	v_cvt_pk_bf16_f32 v36, v54, v55
	v_cvt_pk_bf16_f32 v37, v154, v155
	v_lshl_add_u64 v[38:39], s[78:79], 0, v[112:113]
	global_store_dwordx2 v[38:39], v[36:37], off
	v_cvt_pk_bf16_f32 v36, v118, v119
	v_cvt_pk_bf16_f32 v37, v120, v121
	v_lshl_add_u64 v[38:39], s[80:81], 0, v[112:113]
	global_store_dwordx2 v[38:39], v[36:37], off
	v_cvt_pk_bf16_f32 v36, v122, v123
	v_cvt_pk_bf16_f32 v37, v124, v125
	v_lshl_add_u64 v[38:39], s[82:83], 0, v[112:113]
	global_store_dwordx2 v[38:39], v[36:37], off
	v_cvt_pk_bf16_f32 v36, v110, v111
	v_cvt_pk_bf16_f32 v37, v178, v179
	v_lshl_add_u64 v[38:39], s[84:85], 0, v[112:113]
	v_add_u32_e32 v54, s20, v173
	global_store_dwordx2 v[38:39], v[36:37], off
	v_mad_i64_i32 v[36:37], s[10:11], v54, s22, v[60:61]
	v_add_co_u32_e32 v36, vcc, s2, v36
	v_ashrrev_i32_e32 v55, 31, v54
	s_nop 0
	v_addc_co_u32_e32 v37, vcc, 0, v37, vcc
	s_waitcnt vmcnt(12)
	v_mov_b64_e32 v[106:107], v[246:247]
	v_mov_b64_e32 v[110:111], v[248:249]
	v_mov_b64_e32 v[118:119], v[250:251]
	v_mov_b64_e32 v[116:117], v[254:255]
	ds_read2st64_b64 v[36:39], v174 offset0:16 offset1:80
	s_waitcnt lgkmcnt(0)
	v_lshlrev_b32_e32 v58, 16, v38
	v_add_f32_e32 v58, v12, v58
	v_mul_f32_e32 v58, 0xbfb8aa3b, v58
	v_exp_f32_e32 v58, v58
	v_and_b32_e32 v38, 0xffff0000, v38
	v_add_f32_e32 v38, v13, v38
	v_mul_f32_e32 v38, 0xbfb8aa3b, v38
	v_lshlrev_b32_e32 v103, 16, v39
	v_and_b32_e32 v126, 0xffff0000, v39
	v_add_f32_e32 v39, 1.0, v58
	v_exp_f32_e32 v58, v38
	v_lshlrev_b32_e32 v112, 16, v106
	v_add_f32_e32 v58, 1.0, v58
	v_and_b32_e32 v113, 0xffff0000, v106
	v_lshlrev_b32_e32 v120, 16, v107
	v_and_b32_e32 v121, 0xffff0000, v107
	v_rcp_f32_e32 v106, v39
	v_rcp_f32_e32 v107, v58
	v_add_f32_e32 v58, v14, v103
	v_mul_f32_e32 v58, 0xbfb8aa3b, v58
	v_add_f32_e32 v103, v15, v126
	v_lshlrev_b32_e32 v122, 16, v110
	v_and_b32_e32 v123, 0xffff0000, v110
	v_exp_f32_e32 v58, v58
	v_mul_f32_e32 v103, 0xbfb8aa3b, v103
	v_lshlrev_b32_e32 v124, 16, v111
	v_and_b32_e32 v125, 0xffff0000, v111
	v_pk_add_f32 v[38:39], v[108:109], v[112:113] neg_lo:[0,1] neg_hi:[0,1]
	v_pk_add_f32 v[108:109], v[114:115], v[122:123] neg_lo:[0,1] neg_hi:[0,1]
	v_pk_add_f32 v[110:111], v[106:107], -1.0 op_sel_hi:[1,0]
	v_exp_f32_e32 v103, v103
	v_pk_fma_f32 v[108:109], v[20:21], v[108:109], v[122:123]
	v_pk_fma_f32 v[110:111], v[28:29], v[110:111], 1.0 op_sel_hi:[1,1,0]
	v_pk_fma_f32 v[38:39], v[16:17], v[38:39], v[112:113]
	v_pk_mul_f32 v[112:113], v[24:25], v[108:109]
	v_pk_mul_f32 v[108:109], v[108:109], v[110:111]
	v_add_f32_e32 v58, 1.0, v58
	v_pk_mul_f32 v[110:111], v[38:39], v[108:109]
	v_pk_add_f32 v[46:47], v[46:47], v[124:125] neg_lo:[0,1] neg_hi:[0,1]
	v_fma_f32 v127, v32, v110, 0
	v_rcp_f32_e32 v110, v58
	v_add_f32_e32 v58, 1.0, v103
	v_fmac_f32_e32 v127, v33, v111
	v_rcp_f32_e32 v111, v58
	v_pk_fma_f32 v[46:47], v[22:23], v[46:47], v[124:125]
	v_pk_mul_f32 v[122:123], v[112:113], v[112:113]
	v_pk_add_f32 v[44:45], v[44:45], v[120:121] neg_lo:[0,1] neg_hi:[0,1]
	v_pk_mul_f32 v[114:115], v[26:27], v[46:47]
	v_pk_fma_f32 v[44:45], v[18:19], v[44:45], v[120:121]
	v_pk_mul_f32 v[120:121], v[114:115], v[114:115]
	v_add_f32_e32 v58, v122, v123
	v_add_f32_e32 v58, v58, v120
	v_add_f32_e32 v58, v121, v58
	v_pk_add_f32 v[120:121], v[110:111], -1.0 op_sel_hi:[1,0]
	s_nop 0
	v_pk_fma_f32 v[120:121], v[30:31], v[120:121], 1.0 op_sel_hi:[1,1,0]
	v_add_f32_dpp v58, v58, v58 quad_perm:[1,0,3,2] row_mask:0xf bank_mask:0xf bound_ctrl:1
	v_pk_mul_f32 v[46:47], v[46:47], v[120:121]
	s_nop 0
	v_pk_mul_f32 v[120:121], v[44:45], v[46:47]
	v_add_f32_dpp v58, v58, v58 quad_perm:[2,3,0,1] row_mask:0xf bank_mask:0xf bound_ctrl:1
	v_fmac_f32_e32 v127, v34, v120
	v_fmac_f32_e32 v127, v35, v121
	v_add_f32_dpp v58, v58, v58 row_half_mirror row_mask:0xf bank_mask:0xf bound_ctrl:1
	s_nop 0
	v_add_f32_dpp v120, v127, v127 quad_perm:[1,0,3,2] row_mask:0xf bank_mask:0xf bound_ctrl:1
	v_mov_b32_dpp v103, v58 row_mirror row_mask:0xf bank_mask:0xf bound_ctrl:1
	s_nop 0
	v_add_f32_dpp v120, v120, v120 quad_perm:[2,3,0,1] row_mask:0xf bank_mask:0xf bound_ctrl:1
	s_nop 1
	v_add_f32_dpp v120, v120, v120 row_half_mirror row_mask:0xf bank_mask:0xf bound_ctrl:1
	s_nop 1
	v_mov_b32_dpp v121, v120 row_mirror row_mask:0xf bank_mask:0xf bound_ctrl:1
	s_and_saveexec_b64 s[10:11], s[6:7]
	s_cbranch_execz .LBB0_162
	v_lshlrev_b64 v[122:123], 6, v[54:55]
	v_lshl_add_u64 v[122:123], v[98:99], 0, v[122:123]
	v_add_f32_e32 v55, v120, v121
	global_store_dword v[122:123], v55, off
	s_branch .LBB0_162

	.amdhsa_kernel _Z10hymba_mega6Params
		.amdhsa_group_segment_fixed_size 131072
		.amdhsa_private_segment_fixed_size 0
		.amdhsa_kernarg_size 584
		.amdhsa_user_sgpr_count 2
		.amdhsa_user_sgpr_dispatch_ptr 0
		.amdhsa_user_sgpr_queue_ptr 0
		.amdhsa_user_sgpr_kernarg_segment_ptr 1
		.amdhsa_user_sgpr_dispatch_id 0
		.amdhsa_user_sgpr_kernarg_preload_length 0
		.amdhsa_user_sgpr_kernarg_preload_offset 0
		.amdhsa_user_sgpr_private_segment_size 0
		.amdhsa_uses_dynamic_stack 0
		.amdhsa_enable_private_segment 0
		.amdhsa_system_sgpr_workgroup_id_x 1
		.amdhsa_system_sgpr_workgroup_id_y 0
		.amdhsa_system_sgpr_workgroup_id_z 0
		.amdhsa_system_sgpr_workgroup_info 0
		.amdhsa_system_vgpr_workitem_id 2
		.amdhsa_next_free_vgpr 256
		.amdhsa_next_free_sgpr 100
		.amdhsa_accum_offset 256
		.amdhsa_reserve_vcc 1
		.amdhsa_float_round_mode_32 0
		.amdhsa_float_round_mode_16_64 0
		.amdhsa_float_denorm_mode_32 3
		.amdhsa_float_denorm_mode_16_64 3
		.amdhsa_dx10_clamp 1
		.amdhsa_ieee_mode 1
		.amdhsa_fp16_overflow 0
		.amdhsa_tg_split 0
		.amdhsa_exception_fp_ieee_invalid_op 0
		.amdhsa_exception_fp_denorm_src 0
		.amdhsa_exception_fp_ieee_div_zero 0
		.amdhsa_exception_fp_ieee_overflow 0
		.amdhsa_exception_fp_ieee_underflow 0
		.amdhsa_exception_fp_ieee_inexact 0
		.amdhsa_exception_int_div_zero 0
	.end_amdhsa_kernel

amdhsa.kernels:
  - .agpr_count:     0
    .args:
      - .offset:         0
        .size:           328
        .value_kind:     by_value
      - .offset:         328
        .size:           4
        .value_kind:     hidden_block_count_x
      - .offset:         332
        .size:           4
        .value_kind:     hidden_block_count_y
      - .offset:         336
        .size:           4
        .value_kind:     hidden_block_count_z
      - .offset:         340
        .size:           2
        .value_kind:     hidden_group_size_x
      - .offset:         342
        .size:           2
        .value_kind:     hidden_group_size_y
      - .offset:         344
        .size:           2
        .value_kind:     hidden_group_size_z
      - .offset:         346
        .size:           2
        .value_kind:     hidden_remainder_x
      - .offset:         348
        .size:           2
        .value_kind:     hidden_remainder_y
      - .offset:         350
        .size:           2
        .value_kind:     hidden_remainder_z
      - .offset:         368
        .size:           8
        .value_kind:     hidden_global_offset_x
      - .offset:         376
        .size:           8
        .value_kind:     hidden_global_offset_y
      - .offset:         384
        .size:           8
        .value_kind:     hidden_global_offset_z
      - .offset:         392
        .size:           2
        .value_kind:     hidden_grid_dims
      - .offset:         416
        .size:           8
        .value_kind:     hidden_multigrid_sync_arg
    .group_segment_fixed_size: 131072
    .kernarg_segment_align: 8
    .kernarg_segment_size: 584
    .language:       OpenCL C
    .language_version:
      - 2
      - 0
    .max_flat_workgroup_size: 512
    .name:           _Z10hymba_mega6Params
    .private_segment_fixed_size: 0
    .sgpr_count:     106
    .sgpr_spill_count: 51
    .symbol:         _Z10hymba_mega6Params.kd
    .uniform_work_group_size: 1
    .uses_dynamic_stack: false
    .vgpr_count:     256
    .vgpr_spill_count: 0
    .wavefront_size: 64
